# K-loops of P4/P5/P6 converted from the 8-phase (16-MFMA blocks, 8 barrier intervals per k-tile) to the 4-phase form of the stream loop (32-MFMA blocks, 4 intervals; vmcnt(8)+lgkmcnt(0) before each bar
# speedup vs baseline: 1.0094x; 1.0081x over previous
.LBB0_94:
	s_lshl_b32 s70, s83, 12
	s_add_i32 m0, s43, 0x18000
	v_lshl_add_u64 v[8:9], v[8:9], 0, s[48:49]
	s_lshl_b32 s71, s74, 13
	s_and_b32 s70, s70, 0x3000
	s_waitcnt vmcnt(2)
	s_barrier
	global_load_lds_dwordx4 v[8:9], off
	v_lshl_add_u64 v[6:7], v[6:7], 0, s[48:49]
	s_add_i32 m0, s43, 0x1a000
	s_add_i32 s74, s43, 0x8000
	s_add_i32 vcc_lo, s43, 0xa000
	global_load_lds_dwordx4 v[6:7], off
	v_lshl_add_u64 v[4:5], v[4:5], 0, s[48:49]
	s_mov_b32 m0, s74
	s_add_u32 s40, s40, 0xb0080
	global_load_lds_dwordx4 v[4:5], off
	v_lshl_add_u64 v[2:3], v[2:3], 0, s[48:49]
	s_mov_b32 m0, vcc_lo
	s_addc_u32 s41, s41, 0
	global_load_lds_dwordx4 v[2:3], off
	s_add_i32 m0, s43, 0x1c000
	v_lshl_add_u64 v[2:3], s[40:41], 0, v[130:131]
	global_load_lds_dwordx4 v[2:3], off
	v_lshl_add_u64 v[2:3], s[40:41], 0, v[132:133]
	s_add_i32 m0, s43, 0x1e000
	v_and_b32_e32 v19, 15, v18
	global_load_lds_dwordx4 v[2:3], off
	v_and_b32_e32 v20, 48, v18
	v_lshlrev_b32_e32 v18, 2, v18
	v_lshlrev_b32_e32 v19, 6, v19
	v_and_b32_e32 v18, 32, v18
	v_or_b32_e32 v21, v19, v20
	v_bitop3_b32 v19, v19, v18, v20 bitop3:0x36
	v_or_b32_e32 v143, s70, v19
	s_movk_i32 s70, 0xb00
	v_bitop3_b32 v18, v21, s71, v18 bitop3:0xde
	v_lshrrev_b32_e32 v3, 1, v10
	v_mul_lo_u32 v2, v12, s70
	s_mov_b32 s71, 0xb000
	v_mad_u64_u32 v[2:3], s[40:41], v3, s71, v[2:3]
	v_readlane_b32 s18, v253, 1
	v_readlane_b32 s19, v253, 2
	s_add_u32 s40, s18, s76
	s_addc_u32 s41, s19, s75
	v_lshrrev_b32_e32 v5, 1, v13
	v_mul_lo_u32 v4, v16, s70
	v_or_b32_e32 v2, v2, v11
	v_mad_u64_u32 v[4:5], s[70:71], v5, s71, v[4:5]
	s_add_u32 s36, s18, s36
	s_waitcnt vmcnt(6)
	v_add_lshl_u32 v2, v2, v14, 1
	v_mov_b32_e32 v3, v196
	v_or_b32_e32 v4, v4, v15
	s_addc_u32 s37, s19, s37
	v_lshl_add_u64 v[134:135], s[40:41], 0, v[2:3]
	v_add_lshl_u32 v4, v4, v17, 1
	v_mov_b32_e32 v5, v196
	v_lshl_add_u64 v[138:139], s[36:37], 0, v[2:3]
	v_mov_b32_e32 v2, 0
	v_lshl_add_u64 v[136:137], s[40:41], 0, v[4:5]
	v_lshl_add_u64 v[140:141], s[36:37], 0, v[4:5]
	s_mov_b32 s36, -2
	v_add_u32_e32 v142, 0, v18
	v_mov_b32_e32 v3, v2
	v_mov_b32_e32 v4, v2
	v_mov_b32_e32 v5, v2
	v_mov_b32_e32 v6, v2
	v_mov_b32_e32 v7, v2
	v_mov_b32_e32 v8, v2
	v_mov_b32_e32 v9, v2
	v_mov_b32_e32 v10, v2
	v_mov_b32_e32 v11, v2
	v_mov_b32_e32 v12, v2
	v_mov_b32_e32 v13, v2
	v_mov_b32_e32 v14, v2
	v_mov_b32_e32 v15, v2
	v_mov_b32_e32 v16, v2
	v_mov_b32_e32 v17, v2
	v_mov_b32_e32 v18, v2
	v_mov_b32_e32 v19, v2
	v_mov_b32_e32 v20, v2
	v_mov_b32_e32 v21, v2
	v_mov_b32_e32 v22, v2
	v_mov_b32_e32 v23, v2
	v_mov_b32_e32 v24, v2
	v_mov_b32_e32 v25, v2
	v_mov_b32_e32 v26, v2
	v_mov_b32_e32 v27, v2
	v_mov_b32_e32 v28, v2
	v_mov_b32_e32 v29, v2
	v_mov_b32_e32 v30, v2
	v_mov_b32_e32 v31, v2
	v_mov_b32_e32 v32, v2
	v_mov_b32_e32 v33, v2
	v_mov_b32_e32 v34, v2
	v_mov_b32_e32 v35, v2
	v_mov_b32_e32 v36, v2
	v_mov_b32_e32 v37, v2
	v_mov_b32_e32 v38, v2
	v_mov_b32_e32 v39, v2
	v_mov_b32_e32 v40, v2
	v_mov_b32_e32 v41, v2
	v_mov_b32_e32 v42, v2
	v_mov_b32_e32 v43, v2
	v_mov_b32_e32 v44, v2
	v_mov_b32_e32 v45, v2
	v_mov_b32_e32 v46, v2
	v_mov_b32_e32 v47, v2
	v_mov_b32_e32 v48, v2
	v_mov_b32_e32 v49, v2
	v_mov_b32_e32 v50, v2
	v_mov_b32_e32 v51, v2
	v_mov_b32_e32 v52, v2
	v_mov_b32_e32 v53, v2
	v_mov_b32_e32 v54, v2
	v_mov_b32_e32 v55, v2
	v_mov_b32_e32 v56, v2
	v_mov_b32_e32 v57, v2
	v_mov_b32_e32 v58, v2
	v_mov_b32_e32 v59, v2
	v_mov_b32_e32 v60, v2
	v_mov_b32_e32 v61, v2
	v_mov_b32_e32 v62, v2
	v_mov_b32_e32 v63, v2
	v_mov_b32_e32 v64, v2
	v_mov_b32_e32 v65, v2
	v_mov_b32_e32 v66, v2
	v_mov_b32_e32 v67, v2
	v_mov_b32_e32 v68, v2
	v_mov_b32_e32 v69, v2
	v_mov_b32_e32 v70, v2
	v_mov_b32_e32 v71, v2
	v_mov_b32_e32 v72, v2
	v_mov_b32_e32 v73, v2
	v_mov_b32_e32 v78, v2
	v_mov_b32_e32 v79, v2
	v_mov_b32_e32 v80, v2
	v_mov_b32_e32 v81, v2
	v_mov_b32_e32 v82, v2
	v_mov_b32_e32 v83, v2
	v_mov_b32_e32 v84, v2
	v_mov_b32_e32 v85, v2
	v_mov_b32_e32 v86, v2
	v_mov_b32_e32 v87, v2
	v_mov_b32_e32 v88, v2
	v_mov_b32_e32 v89, v2
	v_mov_b32_e32 v90, v2
	v_mov_b32_e32 v91, v2
	v_mov_b32_e32 v92, v2
	v_mov_b32_e32 v93, v2
	v_mov_b32_e32 v94, v2
	v_mov_b32_e32 v95, v2
	v_mov_b32_e32 v96, v2
	v_mov_b32_e32 v97, v2
	v_mov_b32_e32 v98, v2
	v_mov_b32_e32 v99, v2
	v_mov_b32_e32 v100, v2
	v_mov_b32_e32 v101, v2
	v_mov_b32_e32 v102, v2
	v_mov_b32_e32 v103, v2
	v_mov_b32_e32 v104, v2
	v_mov_b32_e32 v105, v2
	v_mov_b32_e32 v106, v2
	v_mov_b32_e32 v107, v2
	v_mov_b32_e32 v108, v2
	v_mov_b32_e32 v109, v2
	v_mov_b32_e32 v110, v2
	v_mov_b32_e32 v111, v2
	v_mov_b32_e32 v112, v2
	v_mov_b32_e32 v113, v2
	v_mov_b32_e32 v114, v2
	v_mov_b32_e32 v115, v2
	v_mov_b32_e32 v116, v2
	v_mov_b32_e32 v117, v2
	v_mov_b32_e32 v118, v2
	v_mov_b32_e32 v119, v2
	v_mov_b32_e32 v120, v2
	v_mov_b32_e32 v121, v2
	v_mov_b32_e32 v122, v2
	v_mov_b32_e32 v123, v2
	v_mov_b32_e32 v124, v2
	v_mov_b32_e32 v125, v2
	v_mov_b32_e32 v126, v2
	v_mov_b32_e32 v127, v2
	v_mov_b32_e32 v128, v2
	v_mov_b32_e32 v129, v2
	v_mov_b32_e32 v74, v2
	v_mov_b32_e32 v75, v2
	v_mov_b32_e32 v76, v2
	v_mov_b32_e32 v77, v2
	s_mov_b64 s[44:45], 0x4030080
	s_mov_b64 s[76:77], 0x1a00100
	s_mov_b64 s[82:83], 0x3f80100
	s_mov_b64 s[80:81], 0x1ab0100
	s_mov_b64 s[18:19], 0x4030100
	s_mov_b64 s[52:53], 0x1a00180
	s_mov_b64 s[54:55], 0x3f80180
	s_mov_b64 s[56:57], 0x1ab0180
	s_barrier
.LBB0_95:
	v_add_u32_e32 v156, 0x10000, v143
	ds_read_b128 v[144:147], v156
	ds_read_b128 v[148:151], v156 offset:1024
	ds_read_b128 v[152:155], v156 offset:2048
	ds_read_b128 v[156:159], v156 offset:3072
	ds_read_b128 v[160:163], v142
	ds_read_b128 v[164:167], v142 offset:1024
	ds_read_b128 v[168:171], v142 offset:2048
	ds_read_b128 v[172:175], v142 offset:3072
	ds_read_b128 v[176:179], v142 offset:4096
	ds_read_b128 v[180:183], v142 offset:5120
	ds_read_b128 v[184:187], v142 offset:6144
	ds_read_b128 v[188:191], v142 offset:7168
	s_add_i32 s41, 0, 0x10000
	v_lshl_add_u64 v[210:211], v[138:139], 0, s[14:15]
	s_add_i32 s40, s43, 0xc000
	v_lshl_add_u64 v[192:193], v[210:211], 0, s[44:45]
	s_mov_b32 m0, s40
	v_lshl_add_u64 v[212:213], v[140:141], 0, s[14:15]
	s_add_i32 s37, s43, 0xe000
	global_load_lds_dwordx4 v[192:193], off
	v_lshl_add_u64 v[192:193], v[212:213], 0, s[44:45]
	s_mov_b32 m0, s37
	s_nop 0
	global_load_lds_dwordx4 v[192:193], off
	v_add_u32_e32 v197, 0x14000, v143
	ds_read_b128 v[192:195], v197
	ds_read_b128 v[198:201], v197 offset:1024
	ds_read_b128 v[202:205], v197 offset:2048
	ds_read_b128 v[206:209], v197 offset:3072
	s_waitcnt vmcnt(8)
	s_waitcnt lgkmcnt(0)
	s_barrier
	s_setprio 1
	v_mfma_f32_16x16x32_bf16 v[126:129], v[144:147], v[160:163], v[126:129]
	v_mfma_f32_16x16x32_bf16 v[122:125], v[152:155], v[160:163], v[122:125]
	v_mfma_f32_16x16x32_bf16 v[118:121], v[144:147], v[168:171], v[118:121]
	v_mfma_f32_16x16x32_bf16 v[114:117], v[152:155], v[168:171], v[114:117]
	v_mfma_f32_16x16x32_bf16 v[110:113], v[144:147], v[176:179], v[110:113]
	v_mfma_f32_16x16x32_bf16 v[106:109], v[152:155], v[176:179], v[106:109]
	v_mfma_f32_16x16x32_bf16 v[102:105], v[144:147], v[184:187], v[102:105]
	v_mfma_f32_16x16x32_bf16 v[98:101], v[152:155], v[184:187], v[98:101]
	v_mfma_f32_16x16x32_bf16 v[126:129], v[148:151], v[164:167], v[126:129]
	v_mfma_f32_16x16x32_bf16 v[122:125], v[156:159], v[164:167], v[122:125]
	v_mfma_f32_16x16x32_bf16 v[118:121], v[148:151], v[172:175], v[118:121]
	v_mfma_f32_16x16x32_bf16 v[114:117], v[156:159], v[172:175], v[114:117]
	v_mfma_f32_16x16x32_bf16 v[110:113], v[148:151], v[180:183], v[110:113]
	v_mfma_f32_16x16x32_bf16 v[106:109], v[156:159], v[180:183], v[106:109]
	v_mfma_f32_16x16x32_bf16 v[102:105], v[148:151], v[188:191], v[102:105]
	v_mfma_f32_16x16x32_bf16 v[98:101], v[156:159], v[188:191], v[98:101]
	v_mfma_f32_16x16x32_bf16 v[94:97], v[192:195], v[160:163], v[94:97]
	v_mfma_f32_16x16x32_bf16 v[90:93], v[202:205], v[160:163], v[90:93]
	v_mfma_f32_16x16x32_bf16 v[86:89], v[192:195], v[168:171], v[86:89]
	v_mfma_f32_16x16x32_bf16 v[82:85], v[202:205], v[168:171], v[82:85]
	v_mfma_f32_16x16x32_bf16 v[78:81], v[192:195], v[176:179], v[78:81]
	v_mfma_f32_16x16x32_bf16 v[70:73], v[202:205], v[176:179], v[70:73]
	v_mfma_f32_16x16x32_bf16 v[66:69], v[192:195], v[184:187], v[66:69]
	v_mfma_f32_16x16x32_bf16 v[62:65], v[202:205], v[184:187], v[62:65]
	v_mfma_f32_16x16x32_bf16 v[94:97], v[198:201], v[164:167], v[94:97]
	v_mfma_f32_16x16x32_bf16 v[90:93], v[206:209], v[164:167], v[90:93]
	v_mfma_f32_16x16x32_bf16 v[86:89], v[198:201], v[172:175], v[86:89]
	v_mfma_f32_16x16x32_bf16 v[82:85], v[206:209], v[172:175], v[82:85]
	v_mfma_f32_16x16x32_bf16 v[78:81], v[198:201], v[180:183], v[78:81]
	v_mfma_f32_16x16x32_bf16 v[70:73], v[206:209], v[180:183], v[70:73]
	v_mfma_f32_16x16x32_bf16 v[66:69], v[198:201], v[188:191], v[66:69]
	v_mfma_f32_16x16x32_bf16 v[62:65], v[206:209], v[188:191], v[62:65]
	s_setprio 0
	s_mov_b32 m0, s43
	v_lshl_add_u64 v[218:219], v[210:211], 0, s[82:83]
	s_barrier
	ds_read_b128 v[160:163], v142 offset:16384
	ds_read_b128 v[164:167], v142 offset:17408
	ds_read_b128 v[168:171], v142 offset:18432
	ds_read_b128 v[172:175], v142 offset:19456
	ds_read_b128 v[176:179], v142 offset:20480
	ds_read_b128 v[180:183], v142 offset:21504
	ds_read_b128 v[184:187], v142 offset:22528
	ds_read_b128 v[188:191], v142 offset:23552
	global_load_lds_dwordx4 v[218:219], off
	v_lshl_add_u64 v[218:219], v[212:213], 0, s[82:83]
	s_mov_b32 m0, s73
	s_nop 0
	global_load_lds_dwordx4 v[218:219], off
	s_add_i32 s70, 0, 0x14000
	v_lshl_add_u64 v[214:215], v[134:135], 0, s[14:15]
	s_add_i32 s41, s41, s42
	v_lshl_add_u64 v[216:217], v[214:215], 0, s[76:77]
	s_mov_b32 m0, s41
	s_nop 0
	global_load_lds_dwordx4 v[216:217], off
	v_lshl_add_u64 v[216:217], v[136:137], 0, s[14:15]
	v_lshl_add_u64 v[218:219], v[216:217], 0, s[76:77]
	s_add_i32 m0, s41, 0x2000
	s_nop 0
	global_load_lds_dwordx4 v[218:219], off
	s_add_i32 s41, s70, s42
	v_lshl_add_u64 v[218:219], v[214:215], 0, s[80:81]
	s_mov_b32 m0, s41
	s_nop 0
	global_load_lds_dwordx4 v[218:219], off
	v_lshl_add_u64 v[218:219], v[216:217], 0, s[80:81]
	s_add_i32 m0, s41, 0x2000
	s_nop 0
	global_load_lds_dwordx4 v[218:219], off
	s_waitcnt vmcnt(8)
	s_waitcnt lgkmcnt(0)
	s_barrier
	s_setprio 1
	v_mfma_f32_16x16x32_bf16 v[58:61], v[144:147], v[160:163], v[58:61]
	v_mfma_f32_16x16x32_bf16 v[54:57], v[152:155], v[160:163], v[54:57]
	v_mfma_f32_16x16x32_bf16 v[50:53], v[144:147], v[168:171], v[50:53]
	v_mfma_f32_16x16x32_bf16 v[46:49], v[152:155], v[168:171], v[46:49]
	v_mfma_f32_16x16x32_bf16 v[42:45], v[144:147], v[176:179], v[42:45]
	v_mfma_f32_16x16x32_bf16 v[38:41], v[152:155], v[176:179], v[38:41]
	v_mfma_f32_16x16x32_bf16 v[34:37], v[144:147], v[184:187], v[34:37]
	v_mfma_f32_16x16x32_bf16 v[30:33], v[152:155], v[184:187], v[30:33]
	v_mfma_f32_16x16x32_bf16 v[58:61], v[148:151], v[164:167], v[58:61]
	v_mfma_f32_16x16x32_bf16 v[54:57], v[156:159], v[164:167], v[54:57]
	v_mfma_f32_16x16x32_bf16 v[50:53], v[148:151], v[172:175], v[50:53]
	v_mfma_f32_16x16x32_bf16 v[46:49], v[156:159], v[172:175], v[46:49]
	v_mfma_f32_16x16x32_bf16 v[42:45], v[148:151], v[180:183], v[42:45]
	v_mfma_f32_16x16x32_bf16 v[38:41], v[156:159], v[180:183], v[38:41]
	v_mfma_f32_16x16x32_bf16 v[34:37], v[148:151], v[188:191], v[34:37]
	v_mfma_f32_16x16x32_bf16 v[30:33], v[156:159], v[188:191], v[30:33]
	v_mfma_f32_16x16x32_bf16 v[26:29], v[192:195], v[160:163], v[26:29]
	v_mfma_f32_16x16x32_bf16 v[22:25], v[202:205], v[160:163], v[22:25]
	v_mfma_f32_16x16x32_bf16 v[18:21], v[192:195], v[168:171], v[18:21]
	v_mfma_f32_16x16x32_bf16 v[14:17], v[202:205], v[168:171], v[14:17]
	v_mfma_f32_16x16x32_bf16 v[10:13], v[192:195], v[176:179], v[10:13]
	v_mfma_f32_16x16x32_bf16 v[6:9], v[202:205], v[176:179], v[6:9]
	v_mfma_f32_16x16x32_bf16 v[2:5], v[192:195], v[184:187], v[2:5]
	v_mfma_f32_16x16x32_bf16 v[74:77], v[202:205], v[184:187], v[74:77]
	v_mfma_f32_16x16x32_bf16 v[26:29], v[198:201], v[164:167], v[26:29]
	v_mfma_f32_16x16x32_bf16 v[22:25], v[206:209], v[164:167], v[22:25]
	v_mfma_f32_16x16x32_bf16 v[18:21], v[198:201], v[172:175], v[18:21]
	v_mfma_f32_16x16x32_bf16 v[14:17], v[206:209], v[172:175], v[14:17]
	v_mfma_f32_16x16x32_bf16 v[10:13], v[198:201], v[180:183], v[10:13]
	v_mfma_f32_16x16x32_bf16 v[6:9], v[206:209], v[180:183], v[6:9]
	v_mfma_f32_16x16x32_bf16 v[2:5], v[198:201], v[188:191], v[2:5]
	v_mfma_f32_16x16x32_bf16 v[74:77], v[206:209], v[188:191], v[74:77]
	s_setprio 0
	s_add_i32 s41, 0, 0x18000
	s_barrier
	v_add_u32_e32 v156, 0x18000, v143
	ds_read_b128 v[144:147], v156
	ds_read_b128 v[148:151], v156 offset:1024
	ds_read_b128 v[152:155], v156 offset:2048
	ds_read_b128 v[156:159], v156 offset:3072
	ds_read_b128 v[160:163], v142 offset:32768
	ds_read_b128 v[164:167], v142 offset:33792
	ds_read_b128 v[168:171], v142 offset:34816
	ds_read_b128 v[172:175], v142 offset:35840
	ds_read_b128 v[176:179], v142 offset:36864
	ds_read_b128 v[180:183], v142 offset:37888
	ds_read_b128 v[184:187], v142 offset:38912
	ds_read_b128 v[188:191], v142 offset:39936
	s_mov_b32 m0, s78
	v_lshl_add_u64 v[192:193], v[210:211], 0, s[18:19]
	global_load_lds_dwordx4 v[192:193], off
	v_lshl_add_u64 v[192:193], v[212:213], 0, s[18:19]
	s_mov_b32 m0, s79
	s_nop 0
	global_load_lds_dwordx4 v[192:193], off
	v_add_u32_e32 v197, 0x1c000, v143
	ds_read_b128 v[192:195], v197
	ds_read_b128 v[198:201], v197 offset:1024
	ds_read_b128 v[202:205], v197 offset:2048
	ds_read_b128 v[206:209], v197 offset:3072
	s_waitcnt vmcnt(8)
	s_waitcnt lgkmcnt(0)
	s_barrier
	s_setprio 1
	v_mfma_f32_16x16x32_bf16 v[126:129], v[144:147], v[160:163], v[126:129]
	v_mfma_f32_16x16x32_bf16 v[122:125], v[152:155], v[160:163], v[122:125]
	v_mfma_f32_16x16x32_bf16 v[118:121], v[144:147], v[168:171], v[118:121]
	v_mfma_f32_16x16x32_bf16 v[114:117], v[152:155], v[168:171], v[114:117]
	v_mfma_f32_16x16x32_bf16 v[110:113], v[144:147], v[176:179], v[110:113]
	v_mfma_f32_16x16x32_bf16 v[106:109], v[152:155], v[176:179], v[106:109]
	v_mfma_f32_16x16x32_bf16 v[102:105], v[144:147], v[184:187], v[102:105]
	v_mfma_f32_16x16x32_bf16 v[98:101], v[152:155], v[184:187], v[98:101]
	v_mfma_f32_16x16x32_bf16 v[126:129], v[148:151], v[164:167], v[126:129]
	v_mfma_f32_16x16x32_bf16 v[122:125], v[156:159], v[164:167], v[122:125]
	v_mfma_f32_16x16x32_bf16 v[118:121], v[148:151], v[172:175], v[118:121]
	v_mfma_f32_16x16x32_bf16 v[114:117], v[156:159], v[172:175], v[114:117]
	v_mfma_f32_16x16x32_bf16 v[110:113], v[148:151], v[180:183], v[110:113]
	v_mfma_f32_16x16x32_bf16 v[106:109], v[156:159], v[180:183], v[106:109]
	v_mfma_f32_16x16x32_bf16 v[102:105], v[148:151], v[188:191], v[102:105]
	v_mfma_f32_16x16x32_bf16 v[98:101], v[156:159], v[188:191], v[98:101]
	v_mfma_f32_16x16x32_bf16 v[94:97], v[192:195], v[160:163], v[94:97]
	v_mfma_f32_16x16x32_bf16 v[90:93], v[202:205], v[160:163], v[90:93]
	v_mfma_f32_16x16x32_bf16 v[86:89], v[192:195], v[168:171], v[86:89]
	v_mfma_f32_16x16x32_bf16 v[82:85], v[202:205], v[168:171], v[82:85]
	v_mfma_f32_16x16x32_bf16 v[78:81], v[192:195], v[176:179], v[78:81]
	v_mfma_f32_16x16x32_bf16 v[70:73], v[202:205], v[176:179], v[70:73]
	v_mfma_f32_16x16x32_bf16 v[66:69], v[192:195], v[184:187], v[66:69]
	v_mfma_f32_16x16x32_bf16 v[62:65], v[202:205], v[184:187], v[62:65]
	v_mfma_f32_16x16x32_bf16 v[94:97], v[198:201], v[164:167], v[94:97]
	v_mfma_f32_16x16x32_bf16 v[90:93], v[206:209], v[164:167], v[90:93]
	v_mfma_f32_16x16x32_bf16 v[86:89], v[198:201], v[172:175], v[86:89]
	v_mfma_f32_16x16x32_bf16 v[82:85], v[206:209], v[172:175], v[82:85]
	v_mfma_f32_16x16x32_bf16 v[78:81], v[198:201], v[180:183], v[78:81]
	v_mfma_f32_16x16x32_bf16 v[70:73], v[206:209], v[180:183], v[70:73]
	v_mfma_f32_16x16x32_bf16 v[66:69], v[198:201], v[188:191], v[66:69]
	v_mfma_f32_16x16x32_bf16 v[62:65], v[206:209], v[188:191], v[62:65]
	s_setprio 0
	s_mov_b32 m0, s74
	v_lshl_add_u64 v[210:211], v[210:211], 0, s[54:55]
	s_barrier
	ds_read_b128 v[160:163], v142 offset:49152
	ds_read_b128 v[164:167], v142 offset:50176
	ds_read_b128 v[168:171], v142 offset:51200
	ds_read_b128 v[172:175], v142 offset:52224
	ds_read_b128 v[176:179], v142 offset:53248
	ds_read_b128 v[180:183], v142 offset:54272
	ds_read_b128 v[184:187], v142 offset:55296
	ds_read_b128 v[188:191], v142 offset:56320
	global_load_lds_dwordx4 v[210:211], off
	v_lshl_add_u64 v[210:211], v[212:213], 0, s[54:55]
	s_mov_b32 m0, vcc_lo
	s_nop 0
	global_load_lds_dwordx4 v[210:211], off
	s_add_i32 s70, 0, 0x1c000
	s_add_i32 s41, s41, s42
	v_lshl_add_u64 v[218:219], v[214:215], 0, s[52:53]
	s_mov_b32 m0, s41
	s_nop 0
	global_load_lds_dwordx4 v[218:219], off
	v_lshl_add_u64 v[218:219], v[216:217], 0, s[52:53]
	s_add_i32 m0, s41, 0x2000
	s_nop 0
	global_load_lds_dwordx4 v[218:219], off
	s_add_i32 s41, s70, s42
	v_lshl_add_u64 v[218:219], v[214:215], 0, s[56:57]
	s_mov_b32 m0, s41
	s_nop 0
	global_load_lds_dwordx4 v[218:219], off
	v_lshl_add_u64 v[218:219], v[216:217], 0, s[56:57]
	s_add_i32 m0, s41, 0x2000
	s_nop 0
	global_load_lds_dwordx4 v[218:219], off
	s_waitcnt vmcnt(8)
	s_waitcnt lgkmcnt(0)
	s_barrier
	s_setprio 1
	v_mfma_f32_16x16x32_bf16 v[58:61], v[144:147], v[160:163], v[58:61]
	v_mfma_f32_16x16x32_bf16 v[54:57], v[152:155], v[160:163], v[54:57]
	v_mfma_f32_16x16x32_bf16 v[50:53], v[144:147], v[168:171], v[50:53]
	v_mfma_f32_16x16x32_bf16 v[46:49], v[152:155], v[168:171], v[46:49]
	v_mfma_f32_16x16x32_bf16 v[42:45], v[144:147], v[176:179], v[42:45]
	v_mfma_f32_16x16x32_bf16 v[38:41], v[152:155], v[176:179], v[38:41]
	v_mfma_f32_16x16x32_bf16 v[34:37], v[144:147], v[184:187], v[34:37]
	v_mfma_f32_16x16x32_bf16 v[30:33], v[152:155], v[184:187], v[30:33]
	v_mfma_f32_16x16x32_bf16 v[58:61], v[148:151], v[164:167], v[58:61]
	v_mfma_f32_16x16x32_bf16 v[54:57], v[156:159], v[164:167], v[54:57]
	v_mfma_f32_16x16x32_bf16 v[50:53], v[148:151], v[172:175], v[50:53]
	v_mfma_f32_16x16x32_bf16 v[46:49], v[156:159], v[172:175], v[46:49]
	v_mfma_f32_16x16x32_bf16 v[42:45], v[148:151], v[180:183], v[42:45]
	v_mfma_f32_16x16x32_bf16 v[38:41], v[156:159], v[180:183], v[38:41]
	v_mfma_f32_16x16x32_bf16 v[34:37], v[148:151], v[188:191], v[34:37]
	v_mfma_f32_16x16x32_bf16 v[30:33], v[156:159], v[188:191], v[30:33]
	v_mfma_f32_16x16x32_bf16 v[26:29], v[192:195], v[160:163], v[26:29]
	v_mfma_f32_16x16x32_bf16 v[22:25], v[202:205], v[160:163], v[22:25]
	v_mfma_f32_16x16x32_bf16 v[18:21], v[192:195], v[168:171], v[18:21]
	v_mfma_f32_16x16x32_bf16 v[14:17], v[202:205], v[168:171], v[14:17]
	v_mfma_f32_16x16x32_bf16 v[10:13], v[192:195], v[176:179], v[10:13]
	v_mfma_f32_16x16x32_bf16 v[6:9], v[202:205], v[176:179], v[6:9]
	v_mfma_f32_16x16x32_bf16 v[2:5], v[192:195], v[184:187], v[2:5]
	v_mfma_f32_16x16x32_bf16 v[74:77], v[202:205], v[184:187], v[74:77]
	v_mfma_f32_16x16x32_bf16 v[26:29], v[198:201], v[164:167], v[26:29]
	v_mfma_f32_16x16x32_bf16 v[22:25], v[206:209], v[164:167], v[22:25]
	v_mfma_f32_16x16x32_bf16 v[18:21], v[198:201], v[172:175], v[18:21]
	v_mfma_f32_16x16x32_bf16 v[14:17], v[206:209], v[172:175], v[14:17]
	v_mfma_f32_16x16x32_bf16 v[10:13], v[198:201], v[180:183], v[10:13]
	v_mfma_f32_16x16x32_bf16 v[6:9], v[206:209], v[180:183], v[6:9]
	v_mfma_f32_16x16x32_bf16 v[2:5], v[198:201], v[188:191], v[2:5]
	v_mfma_f32_16x16x32_bf16 v[74:77], v[206:209], v[188:191], v[74:77]
	s_setprio 0
	s_add_i32 s36, s36, 2
	v_lshl_add_u64 v[134:135], v[134:135], 0, s[98:99]
	v_lshl_add_u64 v[136:137], v[136:137], 0, s[98:99]
	v_lshl_add_u64 v[138:139], v[138:139], 0, s[98:99]
	s_cmp_gt_u32 s36, 39
	v_lshl_add_u64 v[140:141], v[140:141], 0, s[98:99]
	s_barrier
	s_cbranch_scc0 .LBB0_95
	s_add_u32 s16, s16, 0xb1580
	v_add_u32_e32 v143, 0, v143
	s_addc_u32 s17, s17, 0
	s_mov_b32 m0, s40
	v_add_u32_e32 v148, 0x10000, v143
	v_lshl_add_u64 v[130:131], s[16:17], 0, v[130:131]
	ds_read_b128 v[134:137], v148
	ds_read_b128 v[138:141], v148 offset:1024
	ds_read_b128 v[144:147], v148 offset:2048
	ds_read_b128 v[148:151], v148 offset:3072
	ds_read_b128 v[152:155], v142
	ds_read_b128 v[156:159], v142 offset:1024
	ds_read_b128 v[160:163], v142 offset:2048
	ds_read_b128 v[164:167], v142 offset:3072
	ds_read_b128 v[168:171], v142 offset:4096
	ds_read_b128 v[172:175], v142 offset:5120
	ds_read_b128 v[176:179], v142 offset:6144
	ds_read_b128 v[180:183], v142 offset:7168
	global_load_lds_dwordx4 v[130:131], off
	v_lshl_add_u64 v[130:131], s[16:17], 0, v[132:133]
	s_mov_b32 m0, s37
	s_nop 0
	global_load_lds_dwordx4 v[130:131], off
	s_barrier
	s_waitcnt lgkmcnt(0)
	s_setprio 1
	s_waitcnt lgkmcnt(0)
	v_mfma_f32_16x16x32_bf16 v[126:129], v[134:137], v[152:155], v[126:129]
	v_mfma_f32_16x16x32_bf16 v[122:125], v[144:147], v[152:155], v[122:125]
	v_mfma_f32_16x16x32_bf16 v[118:121], v[134:137], v[160:163], v[118:121]
	v_mfma_f32_16x16x32_bf16 v[114:117], v[144:147], v[160:163], v[114:117]
	v_mfma_f32_16x16x32_bf16 v[102:105], v[134:137], v[176:179], v[102:105]
	v_mfma_f32_16x16x32_bf16 v[126:129], v[138:141], v[156:159], v[126:129]
	v_mfma_f32_16x16x32_bf16 v[122:125], v[148:151], v[156:159], v[122:125]
	v_mfma_f32_16x16x32_bf16 v[118:121], v[138:141], v[164:167], v[118:121]
	v_mfma_f32_16x16x32_bf16 v[114:117], v[148:151], v[164:167], v[114:117]
	v_mfma_f32_16x16x32_bf16 v[110:113], v[134:137], v[168:171], v[110:113]
	v_mfma_f32_16x16x32_bf16 v[106:109], v[144:147], v[168:171], v[106:109]
	v_mfma_f32_16x16x32_bf16 v[102:105], v[138:141], v[180:183], v[102:105]
	v_mfma_f32_16x16x32_bf16 v[98:101], v[144:147], v[176:179], v[98:101]
	v_mfma_f32_16x16x32_bf16 v[110:113], v[138:141], v[172:175], v[110:113]
	v_mfma_f32_16x16x32_bf16 v[106:109], v[148:151], v[172:175], v[106:109]
	v_mfma_f32_16x16x32_bf16 v[130:133], v[148:151], v[180:183], v[98:101]
	s_setprio 0
	v_add_u32_e32 v192, 0x14000, v143
	s_barrier
	s_nop 1
	ds_read_b128 v[98:101], v192
	ds_read_b128 v[184:187], v192 offset:1024
	ds_read_b128 v[188:191], v192 offset:2048
	ds_read_b128 v[192:195], v192 offset:3072
	s_barrier
	s_waitcnt lgkmcnt(0)
	s_setprio 1
	s_waitcnt lgkmcnt(0)
	v_mfma_f32_16x16x32_bf16 v[94:97], v[98:101], v[152:155], v[94:97]
	v_mfma_f32_16x16x32_bf16 v[82:85], v[188:191], v[160:163], v[82:85]
	v_mfma_f32_16x16x32_bf16 v[62:65], v[188:191], v[176:179], v[62:65]
	v_mfma_f32_16x16x32_bf16 v[94:97], v[184:187], v[156:159], v[94:97]
	v_mfma_f32_16x16x32_bf16 v[90:93], v[188:191], v[152:155], v[90:93]
	v_mfma_f32_16x16x32_bf16 v[86:89], v[98:101], v[160:163], v[86:89]
	v_mfma_f32_16x16x32_bf16 v[82:85], v[192:195], v[164:167], v[82:85]
	v_mfma_f32_16x16x32_bf16 v[78:81], v[98:101], v[168:171], v[78:81]
	v_mfma_f32_16x16x32_bf16 v[70:73], v[188:191], v[168:171], v[70:73]
	v_mfma_f32_16x16x32_bf16 v[66:69], v[98:101], v[176:179], v[66:69]
	v_mfma_f32_16x16x32_bf16 v[62:65], v[192:195], v[180:183], v[62:65]
	v_mfma_f32_16x16x32_bf16 v[198:201], v[192:195], v[156:159], v[90:93]
	v_mfma_f32_16x16x32_bf16 v[86:89], v[184:187], v[164:167], v[86:89]
	v_mfma_f32_16x16x32_bf16 v[164:167], v[184:187], v[172:175], v[78:81]
	v_mfma_f32_16x16x32_bf16 v[168:171], v[192:195], v[172:175], v[70:73]
	v_mfma_f32_16x16x32_bf16 v[66:69], v[184:187], v[180:183], v[66:69]
	s_setprio 0
	s_barrier
	ds_read_b128 v[70:73], v142 offset:16384
	ds_read_b128 v[78:81], v142 offset:17408
	ds_read_b128 v[90:93], v142 offset:18432
	ds_read_b128 v[152:155], v142 offset:19456
	ds_read_b128 v[156:159], v142 offset:20480
	ds_read_b128 v[160:163], v142 offset:21504
	ds_read_b128 v[172:175], v142 offset:22528
	ds_read_b128 v[176:179], v142 offset:23552
	s_waitcnt vmcnt(4)
	s_barrier
	s_waitcnt lgkmcnt(0)
	s_setprio 1
	s_waitcnt lgkmcnt(0)
	v_mfma_f32_16x16x32_bf16 v[58:61], v[134:137], v[70:73], v[58:61]
	v_mfma_f32_16x16x32_bf16 v[54:57], v[144:147], v[70:73], v[54:57]
	v_mfma_f32_16x16x32_bf16 v[50:53], v[134:137], v[90:93], v[50:53]
	v_mfma_f32_16x16x32_bf16 v[42:45], v[134:137], v[156:159], v[42:45]
	v_mfma_f32_16x16x32_bf16 v[34:37], v[134:137], v[172:175], v[34:37]
	v_mfma_f32_16x16x32_bf16 v[58:61], v[138:141], v[78:81], v[58:61]
	v_mfma_f32_16x16x32_bf16 v[54:57], v[148:151], v[78:81], v[54:57]
	v_mfma_f32_16x16x32_bf16 v[50:53], v[138:141], v[152:155], v[50:53]
	v_mfma_f32_16x16x32_bf16 v[46:49], v[144:147], v[90:93], v[46:49]
	v_mfma_f32_16x16x32_bf16 v[42:45], v[138:141], v[160:163], v[42:45]
	v_mfma_f32_16x16x32_bf16 v[38:41], v[144:147], v[156:159], v[38:41]
	v_mfma_f32_16x16x32_bf16 v[34:37], v[138:141], v[176:179], v[34:37]
	v_mfma_f32_16x16x32_bf16 v[30:33], v[144:147], v[172:175], v[30:33]
	v_mfma_f32_16x16x32_bf16 v[180:183], v[148:151], v[152:155], v[46:49]
	v_mfma_f32_16x16x32_bf16 v[202:205], v[148:151], v[160:163], v[38:41]
	v_mfma_f32_16x16x32_bf16 v[134:137], v[148:151], v[176:179], v[30:33]
	s_setprio 0
	s_setprio 1
	v_mfma_f32_16x16x32_bf16 v[26:29], v[98:101], v[70:73], v[26:29]
	v_mfma_f32_16x16x32_bf16 v[18:21], v[98:101], v[90:93], v[18:21]
	v_mfma_f32_16x16x32_bf16 v[10:13], v[98:101], v[156:159], v[10:13]
	v_mfma_f32_16x16x32_bf16 v[6:9], v[188:191], v[156:159], v[6:9]
	v_mfma_f32_16x16x32_bf16 v[2:5], v[98:101], v[172:175], v[2:5]
	v_mfma_f32_16x16x32_bf16 v[26:29], v[184:187], v[78:81], v[26:29]
	v_mfma_f32_16x16x32_bf16 v[22:25], v[188:191], v[70:73], v[22:25]
	v_mfma_f32_16x16x32_bf16 v[18:21], v[184:187], v[152:155], v[18:21]
	v_mfma_f32_16x16x32_bf16 v[14:17], v[188:191], v[90:93], v[14:17]
	v_mfma_f32_16x16x32_bf16 v[10:13], v[184:187], v[160:163], v[10:13]
	v_mfma_f32_16x16x32_bf16 v[206:209], v[192:195], v[160:163], v[6:9]
	v_mfma_f32_16x16x32_bf16 v[2:5], v[184:187], v[176:179], v[2:5]
	v_mfma_f32_16x16x32_bf16 v[6:9], v[188:191], v[172:175], v[74:77]
	v_mfma_f32_16x16x32_bf16 v[138:141], v[192:195], v[78:81], v[22:25]
	v_mfma_f32_16x16x32_bf16 v[144:147], v[192:195], v[152:155], v[14:17]
	v_mfma_f32_16x16x32_bf16 v[172:175], v[192:195], v[176:179], v[6:9]
	s_setprio 0
	v_add_u32_e32 v22, 0x18000, v143
	s_barrier
	s_nop 1
	ds_read_b128 v[6:9], v22
	ds_read_b128 v[14:17], v22 offset:1024
	ds_read_b128 v[176:179], v22 offset:2048
	ds_read_b128 v[184:187], v22 offset:3072
	ds_read_b128 v[22:25], v142 offset:32768
	ds_read_b128 v[30:33], v142 offset:33792
	ds_read_b128 v[38:41], v142 offset:34816
	ds_read_b128 v[46:49], v142 offset:35840
	ds_read_b128 v[74:77], v142 offset:36864
	ds_read_b128 v[188:191], v142 offset:37888
	ds_read_b128 v[192:195], v142 offset:38912
	ds_read_b128 v[210:213], v142 offset:39936
	s_waitcnt vmcnt(2)
	s_barrier
	s_waitcnt lgkmcnt(0)
	s_setprio 1
	s_waitcnt lgkmcnt(0)
	v_mfma_f32_16x16x32_bf16 v[70:73], v[6:9], v[22:25], v[126:129]
	v_mfma_f32_16x16x32_bf16 v[152:155], v[14:17], v[30:33], v[70:73]
	v_mfma_f32_16x16x32_bf16 v[70:73], v[176:179], v[22:25], v[122:125]
	v_mfma_f32_16x16x32_bf16 v[160:163], v[184:187], v[30:33], v[70:73]
	v_mfma_f32_16x16x32_bf16 v[70:73], v[6:9], v[38:41], v[118:121]
	v_mfma_f32_16x16x32_bf16 v[122:125], v[14:17], v[46:49], v[70:73]
	v_mfma_f32_16x16x32_bf16 v[70:73], v[176:179], v[38:41], v[114:117]
	v_mfma_f32_16x16x32_bf16 v[114:117], v[184:187], v[46:49], v[70:73]
	v_mfma_f32_16x16x32_bf16 v[70:73], v[6:9], v[74:77], v[110:113]
	v_mfma_f32_16x16x32_bf16 v[98:101], v[14:17], v[188:191], v[70:73]
	v_mfma_f32_16x16x32_bf16 v[70:73], v[176:179], v[74:77], v[106:109]
	v_mfma_f32_16x16x32_bf16 v[90:93], v[184:187], v[188:191], v[70:73]
	v_mfma_f32_16x16x32_bf16 v[70:73], v[6:9], v[192:195], v[102:105]
	v_mfma_f32_16x16x32_bf16 v[78:81], v[14:17], v[210:213], v[70:73]
	v_mfma_f32_16x16x32_bf16 v[70:73], v[176:179], v[192:195], v[130:133]
	v_mfma_f32_16x16x32_bf16 v[70:73], v[184:187], v[210:213], v[70:73]
	s_setprio 0
	v_add_u32_e32 v102, 0x1c000, v143
	s_barrier
	ds_read_b128 v[106:109], v102
	ds_read_b128 v[110:113], v102 offset:1024
	ds_read_b128 v[130:133], v102 offset:2048
	ds_read_b128 v[214:217], v102 offset:3072
	s_waitcnt vmcnt(0)
	s_barrier
	s_waitcnt lgkmcnt(0)
	s_setprio 1
	s_waitcnt lgkmcnt(0)
	v_mfma_f32_16x16x32_bf16 v[94:97], v[106:109], v[22:25], v[94:97]
	v_mfma_f32_16x16x32_bf16 v[22:25], v[130:133], v[22:25], v[198:201]
	v_mfma_f32_16x16x32_bf16 v[148:151], v[214:217], v[30:33], v[22:25]
	v_mfma_f32_16x16x32_bf16 v[22:25], v[106:109], v[38:41], v[86:89]
	v_mfma_f32_16x16x32_bf16 v[126:129], v[110:113], v[46:49], v[22:25]
	v_mfma_f32_16x16x32_bf16 v[22:25], v[130:133], v[38:41], v[82:85]
	v_mfma_f32_16x16x32_bf16 v[118:121], v[214:217], v[46:49], v[22:25]
	v_mfma_f32_16x16x32_bf16 v[22:25], v[106:109], v[74:77], v[164:167]
	v_mfma_f32_16x16x32_bf16 v[102:105], v[110:113], v[188:191], v[22:25]
	v_mfma_f32_16x16x32_bf16 v[22:25], v[130:133], v[74:77], v[168:171]
	v_mfma_f32_16x16x32_bf16 v[156:159], v[110:113], v[30:33], v[94:97]
	v_mfma_f32_16x16x32_bf16 v[94:97], v[214:217], v[188:191], v[22:25]
	v_mfma_f32_16x16x32_bf16 v[22:25], v[106:109], v[192:195], v[66:69]
	v_mfma_f32_16x16x32_bf16 v[82:85], v[110:113], v[210:213], v[22:25]
	v_mfma_f32_16x16x32_bf16 v[22:25], v[130:133], v[192:195], v[62:65]
	v_mfma_f32_16x16x32_bf16 v[74:77], v[214:217], v[210:213], v[22:25]
	s_setprio 0
	s_barrier
	ds_read_b128 v[66:69], v142 offset:49152
	ds_read_b128 v[86:89], v142 offset:50176
	ds_read_b128 v[164:167], v142 offset:51200
	ds_read_b128 v[168:171], v142 offset:52224
	ds_read_b128 v[188:191], v142 offset:53248
	ds_read_b128 v[192:195], v142 offset:54272
	ds_read_b128 v[198:201], v142 offset:55296
	ds_read_b128 v[210:213], v142 offset:56320
	s_barrier
	s_waitcnt lgkmcnt(0)
	s_setprio 1
	s_waitcnt lgkmcnt(0)
	v_mfma_f32_16x16x32_bf16 v[22:25], v[6:9], v[66:69], v[58:61]
	v_mfma_f32_16x16x32_bf16 v[62:65], v[14:17], v[86:89], v[22:25]
	v_mfma_f32_16x16x32_bf16 v[22:25], v[176:179], v[66:69], v[54:57]
	v_mfma_f32_16x16x32_bf16 v[54:57], v[184:187], v[86:89], v[22:25]
	v_mfma_f32_16x16x32_bf16 v[22:25], v[6:9], v[164:167], v[50:53]
	v_mfma_f32_16x16x32_bf16 v[46:49], v[14:17], v[168:171], v[22:25]
	v_mfma_f32_16x16x32_bf16 v[22:25], v[176:179], v[164:167], v[180:183]
	v_mfma_f32_16x16x32_bf16 v[38:41], v[184:187], v[168:171], v[22:25]
	v_mfma_f32_16x16x32_bf16 v[22:25], v[6:9], v[188:191], v[42:45]
	v_mfma_f32_16x16x32_bf16 v[6:9], v[6:9], v[198:201], v[34:37]
	v_mfma_f32_16x16x32_bf16 v[30:33], v[14:17], v[192:195], v[22:25]
	v_mfma_f32_16x16x32_bf16 v[22:25], v[176:179], v[188:191], v[202:205]
	v_mfma_f32_16x16x32_bf16 v[14:17], v[14:17], v[210:213], v[6:9]
	v_mfma_f32_16x16x32_bf16 v[6:9], v[176:179], v[198:201], v[134:137]
	v_mfma_f32_16x16x32_bf16 v[22:25], v[184:187], v[192:195], v[22:25]
	v_mfma_f32_16x16x32_bf16 v[6:9], v[184:187], v[210:213], v[6:9]
	s_setprio 0
	s_setprio 1
	v_mfma_f32_16x16x32_bf16 v[26:29], v[106:109], v[66:69], v[26:29]
	v_mfma_f32_16x16x32_bf16 v[58:61], v[110:113], v[86:89], v[26:29]
	v_mfma_f32_16x16x32_bf16 v[26:29], v[130:133], v[66:69], v[138:141]
	v_mfma_f32_16x16x32_bf16 v[18:21], v[106:109], v[164:167], v[18:21]
	v_mfma_f32_16x16x32_bf16 v[10:13], v[106:109], v[188:191], v[10:13]
	v_mfma_f32_16x16x32_bf16 v[50:53], v[214:217], v[86:89], v[26:29]
	v_mfma_f32_16x16x32_bf16 v[42:45], v[110:113], v[168:171], v[18:21]
	v_mfma_f32_16x16x32_bf16 v[18:21], v[130:133], v[164:167], v[144:147]
	v_mfma_f32_16x16x32_bf16 v[26:29], v[110:113], v[192:195], v[10:13]
	v_mfma_f32_16x16x32_bf16 v[10:13], v[130:133], v[188:191], v[206:209]
	v_mfma_f32_16x16x32_bf16 v[2:5], v[106:109], v[198:201], v[2:5]
	v_mfma_f32_16x16x32_bf16 v[34:37], v[214:217], v[168:171], v[18:21]
	v_mfma_f32_16x16x32_bf16 v[18:21], v[214:217], v[192:195], v[10:13]
	v_mfma_f32_16x16x32_bf16 v[10:13], v[110:113], v[210:213], v[2:5]
	v_mfma_f32_16x16x32_bf16 v[2:5], v[130:133], v[198:201], v[172:175]
	v_mfma_f32_16x16x32_bf16 v[2:5], v[214:217], v[210:213], v[2:5]
	s_setprio 0
	s_cmpk_lt_u32 s2, 0x100
	s_movk_i32 s75, 0x410
	s_movk_i32 s76, 0xfbfc
	s_barrier
	s_cbranch_scc0 .LBB0_98
	s_barrier

.LBB0_153:
	s_waitcnt vmcnt(2)
	s_mov_b64 s[68:69], 0
	s_barrier

.LBB0_159:
	s_waitcnt vmcnt(6)
	s_barrier

.LBB0_161:
	v_add_u32_e32 v156, 0x10000, v143
	ds_read_b128 v[144:147], v156
	ds_read_b128 v[148:151], v156 offset:1024
	ds_read_b128 v[152:155], v156 offset:2048
	ds_read_b128 v[156:159], v156 offset:3072
	ds_read_b128 v[160:163], v142
	ds_read_b128 v[164:167], v142 offset:1024
	ds_read_b128 v[168:171], v142 offset:2048
	ds_read_b128 v[172:175], v142 offset:3072
	ds_read_b128 v[176:179], v142 offset:4096
	ds_read_b128 v[180:183], v142 offset:5120
	ds_read_b128 v[184:187], v142 offset:6144
	ds_read_b128 v[188:191], v142 offset:7168
	s_add_i32 s41, 0, 0x10000
	v_lshl_add_u64 v[210:211], v[138:139], 0, s[14:15]
	s_add_i32 s40, s43, 0xc000
	v_lshl_add_u64 v[192:193], v[210:211], 0, s[20:21]
	s_mov_b32 m0, s40
	v_lshl_add_u64 v[212:213], v[140:141], 0, s[14:15]
	s_add_i32 s17, s43, 0xe000
	global_load_lds_dwordx4 v[192:193], off
	v_lshl_add_u64 v[192:193], v[212:213], 0, s[20:21]
	s_mov_b32 m0, s17
	s_nop 0
	global_load_lds_dwordx4 v[192:193], off
	v_add_u32_e32 v197, 0x14000, v143
	ds_read_b128 v[192:195], v197
	ds_read_b128 v[198:201], v197 offset:1024
	ds_read_b128 v[202:205], v197 offset:2048
	ds_read_b128 v[206:209], v197 offset:3072
	s_waitcnt vmcnt(8)
	s_waitcnt lgkmcnt(0)
	s_barrier
	s_setprio 1
	v_mfma_f32_16x16x32_bf16 v[126:129], v[144:147], v[160:163], v[126:129]
	v_mfma_f32_16x16x32_bf16 v[122:125], v[152:155], v[160:163], v[122:125]
	v_mfma_f32_16x16x32_bf16 v[118:121], v[144:147], v[168:171], v[118:121]
	v_mfma_f32_16x16x32_bf16 v[114:117], v[152:155], v[168:171], v[114:117]
	v_mfma_f32_16x16x32_bf16 v[110:113], v[144:147], v[176:179], v[110:113]
	v_mfma_f32_16x16x32_bf16 v[106:109], v[152:155], v[176:179], v[106:109]
	v_mfma_f32_16x16x32_bf16 v[102:105], v[144:147], v[184:187], v[102:105]
	v_mfma_f32_16x16x32_bf16 v[98:101], v[152:155], v[184:187], v[98:101]
	v_mfma_f32_16x16x32_bf16 v[126:129], v[148:151], v[164:167], v[126:129]
	v_mfma_f32_16x16x32_bf16 v[122:125], v[156:159], v[164:167], v[122:125]
	v_mfma_f32_16x16x32_bf16 v[118:121], v[148:151], v[172:175], v[118:121]
	v_mfma_f32_16x16x32_bf16 v[114:117], v[156:159], v[172:175], v[114:117]
	v_mfma_f32_16x16x32_bf16 v[110:113], v[148:151], v[180:183], v[110:113]
	v_mfma_f32_16x16x32_bf16 v[106:109], v[156:159], v[180:183], v[106:109]
	v_mfma_f32_16x16x32_bf16 v[102:105], v[148:151], v[188:191], v[102:105]
	v_mfma_f32_16x16x32_bf16 v[98:101], v[156:159], v[188:191], v[98:101]
	v_mfma_f32_16x16x32_bf16 v[94:97], v[192:195], v[160:163], v[94:97]
	v_mfma_f32_16x16x32_bf16 v[90:93], v[202:205], v[160:163], v[90:93]
	v_mfma_f32_16x16x32_bf16 v[78:81], v[192:195], v[168:171], v[78:81]
	v_mfma_f32_16x16x32_bf16 v[62:65], v[202:205], v[168:171], v[62:65]
	v_mfma_f32_16x16x32_bf16 v[58:61], v[192:195], v[176:179], v[58:61]
	v_mfma_f32_16x16x32_bf16 v[54:57], v[202:205], v[176:179], v[54:57]
	v_mfma_f32_16x16x32_bf16 v[50:53], v[192:195], v[184:187], v[50:53]
	v_mfma_f32_16x16x32_bf16 v[46:49], v[202:205], v[184:187], v[46:49]
	v_mfma_f32_16x16x32_bf16 v[94:97], v[198:201], v[164:167], v[94:97]
	v_mfma_f32_16x16x32_bf16 v[90:93], v[206:209], v[164:167], v[90:93]
	v_mfma_f32_16x16x32_bf16 v[78:81], v[198:201], v[172:175], v[78:81]
	v_mfma_f32_16x16x32_bf16 v[62:65], v[206:209], v[172:175], v[62:65]
	v_mfma_f32_16x16x32_bf16 v[58:61], v[198:201], v[180:183], v[58:61]
	v_mfma_f32_16x16x32_bf16 v[54:57], v[206:209], v[180:183], v[54:57]
	v_mfma_f32_16x16x32_bf16 v[50:53], v[198:201], v[188:191], v[50:53]
	v_mfma_f32_16x16x32_bf16 v[46:49], v[206:209], v[188:191], v[46:49]
	s_setprio 0
	s_mov_b32 m0, s43
	v_lshl_add_u64 v[218:219], v[210:211], 0, s[24:25]
	s_barrier
	ds_read_b128 v[160:163], v142 offset:16384
	ds_read_b128 v[164:167], v142 offset:17408
	ds_read_b128 v[168:171], v142 offset:18432
	ds_read_b128 v[172:175], v142 offset:19456
	ds_read_b128 v[176:179], v142 offset:20480
	ds_read_b128 v[180:183], v142 offset:21504
	ds_read_b128 v[184:187], v142 offset:22528
	ds_read_b128 v[188:191], v142 offset:23552
	global_load_lds_dwordx4 v[218:219], off
	v_lshl_add_u64 v[218:219], v[212:213], 0, s[24:25]
	s_mov_b32 m0, s73
	s_nop 0
	global_load_lds_dwordx4 v[218:219], off
	s_add_i32 s44, 0, 0x14000
	v_lshl_add_u64 v[214:215], v[134:135], 0, s[14:15]
	s_add_i32 s41, s41, s37
	v_lshl_add_u64 v[216:217], v[214:215], 0, s[22:23]
	s_mov_b32 m0, s41
	s_nop 0
	global_load_lds_dwordx4 v[216:217], off
	v_lshl_add_u64 v[216:217], v[136:137], 0, s[14:15]
	v_lshl_add_u64 v[218:219], v[216:217], 0, s[22:23]
	s_add_i32 m0, s41, 0x2000
	s_nop 0
	global_load_lds_dwordx4 v[218:219], off
	s_add_i32 s41, s44, s37
	v_lshl_add_u64 v[218:219], v[214:215], 0, s[26:27]
	s_mov_b32 m0, s41
	s_nop 0
	global_load_lds_dwordx4 v[218:219], off
	v_lshl_add_u64 v[218:219], v[216:217], 0, s[26:27]
	s_add_i32 m0, s41, 0x2000
	s_nop 0
	global_load_lds_dwordx4 v[218:219], off
	s_waitcnt vmcnt(8)
	s_waitcnt lgkmcnt(0)
	s_barrier
	s_setprio 1
	v_mfma_f32_16x16x32_bf16 v[42:45], v[144:147], v[160:163], v[42:45]
	v_mfma_f32_16x16x32_bf16 v[38:41], v[152:155], v[160:163], v[38:41]
	v_mfma_f32_16x16x32_bf16 v[34:37], v[144:147], v[168:171], v[34:37]
	v_mfma_f32_16x16x32_bf16 v[30:33], v[152:155], v[168:171], v[30:33]
	v_mfma_f32_16x16x32_bf16 v[26:29], v[144:147], v[176:179], v[26:29]
	v_mfma_f32_16x16x32_bf16 v[22:25], v[152:155], v[176:179], v[22:25]
	v_mfma_f32_16x16x32_bf16 v[18:21], v[144:147], v[184:187], v[18:21]
	v_mfma_f32_16x16x32_bf16 v[14:17], v[152:155], v[184:187], v[14:17]
	v_mfma_f32_16x16x32_bf16 v[42:45], v[148:151], v[164:167], v[42:45]
	v_mfma_f32_16x16x32_bf16 v[38:41], v[156:159], v[164:167], v[38:41]
	v_mfma_f32_16x16x32_bf16 v[34:37], v[148:151], v[172:175], v[34:37]
	v_mfma_f32_16x16x32_bf16 v[30:33], v[156:159], v[172:175], v[30:33]
	v_mfma_f32_16x16x32_bf16 v[26:29], v[148:151], v[180:183], v[26:29]
	v_mfma_f32_16x16x32_bf16 v[22:25], v[156:159], v[180:183], v[22:25]
	v_mfma_f32_16x16x32_bf16 v[18:21], v[148:151], v[188:191], v[18:21]
	v_mfma_f32_16x16x32_bf16 v[14:17], v[156:159], v[188:191], v[14:17]
	v_mfma_f32_16x16x32_bf16 v[10:13], v[192:195], v[160:163], v[10:13]
	v_mfma_f32_16x16x32_bf16 v[6:9], v[202:205], v[160:163], v[6:9]
	v_mfma_f32_16x16x32_bf16 v[2:5], v[192:195], v[168:171], v[2:5]
	v_mfma_f32_16x16x32_bf16 v[66:69], v[202:205], v[168:171], v[66:69]
	v_mfma_f32_16x16x32_bf16 v[70:73], v[192:195], v[176:179], v[70:73]
	v_mfma_f32_16x16x32_bf16 v[74:77], v[202:205], v[176:179], v[74:77]
	v_mfma_f32_16x16x32_bf16 v[82:85], v[192:195], v[184:187], v[82:85]
	v_mfma_f32_16x16x32_bf16 v[86:89], v[202:205], v[184:187], v[86:89]
	v_mfma_f32_16x16x32_bf16 v[10:13], v[198:201], v[164:167], v[10:13]
	v_mfma_f32_16x16x32_bf16 v[6:9], v[206:209], v[164:167], v[6:9]
	v_mfma_f32_16x16x32_bf16 v[2:5], v[198:201], v[172:175], v[2:5]
	v_mfma_f32_16x16x32_bf16 v[66:69], v[206:209], v[172:175], v[66:69]
	v_mfma_f32_16x16x32_bf16 v[70:73], v[198:201], v[180:183], v[70:73]
	v_mfma_f32_16x16x32_bf16 v[74:77], v[206:209], v[180:183], v[74:77]
	v_mfma_f32_16x16x32_bf16 v[82:85], v[198:201], v[188:191], v[82:85]
	v_mfma_f32_16x16x32_bf16 v[86:89], v[206:209], v[188:191], v[86:89]
	s_setprio 0
	s_add_i32 s41, 0, 0x18000
	s_barrier
	v_add_u32_e32 v156, 0x18000, v143
	ds_read_b128 v[144:147], v156
	ds_read_b128 v[148:151], v156 offset:1024
	ds_read_b128 v[152:155], v156 offset:2048
	ds_read_b128 v[156:159], v156 offset:3072
	ds_read_b128 v[160:163], v142 offset:32768
	ds_read_b128 v[164:167], v142 offset:33792
	ds_read_b128 v[168:171], v142 offset:34816
	ds_read_b128 v[172:175], v142 offset:35840
	ds_read_b128 v[176:179], v142 offset:36864
	ds_read_b128 v[180:183], v142 offset:37888
	ds_read_b128 v[184:187], v142 offset:38912
	ds_read_b128 v[188:191], v142 offset:39936
	s_mov_b32 m0, s79
	v_lshl_add_u64 v[192:193], v[210:211], 0, s[28:29]
	global_load_lds_dwordx4 v[192:193], off
	v_lshl_add_u64 v[192:193], v[212:213], 0, s[28:29]
	s_mov_b32 m0, s78
	s_nop 0
	global_load_lds_dwordx4 v[192:193], off
	v_add_u32_e32 v197, 0x1c000, v143
	ds_read_b128 v[192:195], v197
	ds_read_b128 v[198:201], v197 offset:1024
	ds_read_b128 v[202:205], v197 offset:2048
	ds_read_b128 v[206:209], v197 offset:3072
	s_waitcnt vmcnt(8)
	s_waitcnt lgkmcnt(0)
	s_barrier
	s_setprio 1
	v_mfma_f32_16x16x32_bf16 v[126:129], v[144:147], v[160:163], v[126:129]
	v_mfma_f32_16x16x32_bf16 v[122:125], v[152:155], v[160:163], v[122:125]
	v_mfma_f32_16x16x32_bf16 v[118:121], v[144:147], v[168:171], v[118:121]
	v_mfma_f32_16x16x32_bf16 v[114:117], v[152:155], v[168:171], v[114:117]
	v_mfma_f32_16x16x32_bf16 v[110:113], v[144:147], v[176:179], v[110:113]
	v_mfma_f32_16x16x32_bf16 v[106:109], v[152:155], v[176:179], v[106:109]
	v_mfma_f32_16x16x32_bf16 v[102:105], v[144:147], v[184:187], v[102:105]
	v_mfma_f32_16x16x32_bf16 v[98:101], v[152:155], v[184:187], v[98:101]
	v_mfma_f32_16x16x32_bf16 v[126:129], v[148:151], v[164:167], v[126:129]
	v_mfma_f32_16x16x32_bf16 v[122:125], v[156:159], v[164:167], v[122:125]
	v_mfma_f32_16x16x32_bf16 v[118:121], v[148:151], v[172:175], v[118:121]
	v_mfma_f32_16x16x32_bf16 v[114:117], v[156:159], v[172:175], v[114:117]
	v_mfma_f32_16x16x32_bf16 v[110:113], v[148:151], v[180:183], v[110:113]
	v_mfma_f32_16x16x32_bf16 v[106:109], v[156:159], v[180:183], v[106:109]
	v_mfma_f32_16x16x32_bf16 v[102:105], v[148:151], v[188:191], v[102:105]
	v_mfma_f32_16x16x32_bf16 v[98:101], v[156:159], v[188:191], v[98:101]
	v_mfma_f32_16x16x32_bf16 v[94:97], v[192:195], v[160:163], v[94:97]
	v_mfma_f32_16x16x32_bf16 v[90:93], v[202:205], v[160:163], v[90:93]
	v_mfma_f32_16x16x32_bf16 v[78:81], v[192:195], v[168:171], v[78:81]
	v_mfma_f32_16x16x32_bf16 v[62:65], v[202:205], v[168:171], v[62:65]
	v_mfma_f32_16x16x32_bf16 v[58:61], v[192:195], v[176:179], v[58:61]
	v_mfma_f32_16x16x32_bf16 v[54:57], v[202:205], v[176:179], v[54:57]
	v_mfma_f32_16x16x32_bf16 v[50:53], v[192:195], v[184:187], v[50:53]
	v_mfma_f32_16x16x32_bf16 v[46:49], v[202:205], v[184:187], v[46:49]
	v_mfma_f32_16x16x32_bf16 v[94:97], v[198:201], v[164:167], v[94:97]
	v_mfma_f32_16x16x32_bf16 v[90:93], v[206:209], v[164:167], v[90:93]
	v_mfma_f32_16x16x32_bf16 v[78:81], v[198:201], v[172:175], v[78:81]
	v_mfma_f32_16x16x32_bf16 v[62:65], v[206:209], v[172:175], v[62:65]
	v_mfma_f32_16x16x32_bf16 v[58:61], v[198:201], v[180:183], v[58:61]
	v_mfma_f32_16x16x32_bf16 v[54:57], v[206:209], v[180:183], v[54:57]
	v_mfma_f32_16x16x32_bf16 v[50:53], v[198:201], v[188:191], v[50:53]
	v_mfma_f32_16x16x32_bf16 v[46:49], v[206:209], v[188:191], v[46:49]
	s_setprio 0
	s_mov_b32 m0, s68
	v_lshl_add_u64 v[210:211], v[210:211], 0, s[34:35]
	s_barrier
	ds_read_b128 v[160:163], v142 offset:49152
	ds_read_b128 v[164:167], v142 offset:50176
	ds_read_b128 v[168:171], v142 offset:51200
	ds_read_b128 v[172:175], v142 offset:52224
	ds_read_b128 v[176:179], v142 offset:53248
	ds_read_b128 v[180:183], v142 offset:54272
	ds_read_b128 v[184:187], v142 offset:55296
	ds_read_b128 v[188:191], v142 offset:56320
	global_load_lds_dwordx4 v[210:211], off
	v_lshl_add_u64 v[210:211], v[212:213], 0, s[34:35]
	s_mov_b32 m0, s69
	s_nop 0
	global_load_lds_dwordx4 v[210:211], off
	s_add_i32 s44, 0, 0x1c000
	s_add_i32 s41, s41, s37
	v_lshl_add_u64 v[218:219], v[214:215], 0, s[30:31]
	s_mov_b32 m0, s41
	s_nop 0
	global_load_lds_dwordx4 v[218:219], off
	v_lshl_add_u64 v[218:219], v[216:217], 0, s[30:31]
	s_add_i32 m0, s41, 0x2000
	s_nop 0
	global_load_lds_dwordx4 v[218:219], off
	s_add_i32 s41, s44, s37
	v_lshl_add_u64 v[218:219], v[214:215], 0, s[92:93]
	s_mov_b32 m0, s41
	s_nop 0
	global_load_lds_dwordx4 v[218:219], off
	v_lshl_add_u64 v[218:219], v[216:217], 0, s[92:93]
	s_add_i32 m0, s41, 0x2000
	s_nop 0
	global_load_lds_dwordx4 v[218:219], off
	s_waitcnt vmcnt(8)
	s_waitcnt lgkmcnt(0)
	s_barrier
	s_setprio 1
	v_mfma_f32_16x16x32_bf16 v[42:45], v[144:147], v[160:163], v[42:45]
	v_mfma_f32_16x16x32_bf16 v[38:41], v[152:155], v[160:163], v[38:41]
	v_mfma_f32_16x16x32_bf16 v[34:37], v[144:147], v[168:171], v[34:37]
	v_mfma_f32_16x16x32_bf16 v[30:33], v[152:155], v[168:171], v[30:33]
	v_mfma_f32_16x16x32_bf16 v[26:29], v[144:147], v[176:179], v[26:29]
	v_mfma_f32_16x16x32_bf16 v[22:25], v[152:155], v[176:179], v[22:25]
	v_mfma_f32_16x16x32_bf16 v[18:21], v[144:147], v[184:187], v[18:21]
	v_mfma_f32_16x16x32_bf16 v[14:17], v[152:155], v[184:187], v[14:17]
	v_mfma_f32_16x16x32_bf16 v[42:45], v[148:151], v[164:167], v[42:45]
	v_mfma_f32_16x16x32_bf16 v[38:41], v[156:159], v[164:167], v[38:41]
	v_mfma_f32_16x16x32_bf16 v[34:37], v[148:151], v[172:175], v[34:37]
	v_mfma_f32_16x16x32_bf16 v[30:33], v[156:159], v[172:175], v[30:33]
	v_mfma_f32_16x16x32_bf16 v[26:29], v[148:151], v[180:183], v[26:29]
	v_mfma_f32_16x16x32_bf16 v[22:25], v[156:159], v[180:183], v[22:25]
	v_mfma_f32_16x16x32_bf16 v[18:21], v[148:151], v[188:191], v[18:21]
	v_mfma_f32_16x16x32_bf16 v[14:17], v[156:159], v[188:191], v[14:17]
	v_mfma_f32_16x16x32_bf16 v[10:13], v[192:195], v[160:163], v[10:13]
	v_mfma_f32_16x16x32_bf16 v[6:9], v[202:205], v[160:163], v[6:9]
	v_mfma_f32_16x16x32_bf16 v[2:5], v[192:195], v[168:171], v[2:5]
	v_mfma_f32_16x16x32_bf16 v[66:69], v[202:205], v[168:171], v[66:69]
	v_mfma_f32_16x16x32_bf16 v[70:73], v[192:195], v[176:179], v[70:73]
	v_mfma_f32_16x16x32_bf16 v[74:77], v[202:205], v[176:179], v[74:77]
	v_mfma_f32_16x16x32_bf16 v[82:85], v[192:195], v[184:187], v[82:85]
	v_mfma_f32_16x16x32_bf16 v[86:89], v[202:205], v[184:187], v[86:89]
	v_mfma_f32_16x16x32_bf16 v[10:13], v[198:201], v[164:167], v[10:13]
	v_mfma_f32_16x16x32_bf16 v[6:9], v[206:209], v[164:167], v[6:9]
	v_mfma_f32_16x16x32_bf16 v[2:5], v[198:201], v[172:175], v[2:5]
	v_mfma_f32_16x16x32_bf16 v[66:69], v[206:209], v[172:175], v[66:69]
	v_mfma_f32_16x16x32_bf16 v[70:73], v[198:201], v[180:183], v[70:73]
	v_mfma_f32_16x16x32_bf16 v[74:77], v[206:209], v[180:183], v[74:77]
	v_mfma_f32_16x16x32_bf16 v[82:85], v[198:201], v[188:191], v[82:85]
	v_mfma_f32_16x16x32_bf16 v[86:89], v[206:209], v[188:191], v[86:89]
	s_setprio 0
	s_add_i32 s16, s16, 2
	v_lshl_add_u64 v[134:135], v[134:135], 0, s[98:99]
	v_lshl_add_u64 v[136:137], v[136:137], 0, s[98:99]
	v_lshl_add_u64 v[138:139], v[138:139], 0, s[98:99]
	s_cmp_gt_u32 s16, 11
	v_lshl_add_u64 v[140:141], v[140:141], 0, s[98:99]
	s_barrier
	s_cbranch_scc0 .LBB0_161
	s_add_u32 s0, s0, 0x40780
	v_add_u32_e32 v143, 0, v143
	s_addc_u32 s1, s1, 0
	s_mov_b32 m0, s40
	v_add_u32_e32 v148, 0x10000, v143
	v_lshl_add_u64 v[130:131], s[0:1], 0, v[130:131]
	ds_read_b128 v[134:137], v148
	ds_read_b128 v[138:141], v148 offset:1024
	ds_read_b128 v[144:147], v148 offset:2048
	ds_read_b128 v[148:151], v148 offset:3072
	ds_read_b128 v[152:155], v142
	ds_read_b128 v[156:159], v142 offset:1024
	ds_read_b128 v[160:163], v142 offset:2048
	ds_read_b128 v[164:167], v142 offset:3072
	ds_read_b128 v[168:171], v142 offset:4096
	ds_read_b128 v[172:175], v142 offset:5120
	ds_read_b128 v[176:179], v142 offset:6144
	ds_read_b128 v[180:183], v142 offset:7168
	global_load_lds_dwordx4 v[130:131], off
	v_lshl_add_u64 v[130:131], s[0:1], 0, v[132:133]
	s_mov_b32 m0, s17
	s_nop 0
	global_load_lds_dwordx4 v[130:131], off
	s_barrier
	s_waitcnt lgkmcnt(0)
	s_setprio 1
	s_waitcnt lgkmcnt(0)
	v_mfma_f32_16x16x32_bf16 v[126:129], v[134:137], v[152:155], v[126:129]
	v_mfma_f32_16x16x32_bf16 v[122:125], v[144:147], v[152:155], v[122:125]
	v_mfma_f32_16x16x32_bf16 v[118:121], v[134:137], v[160:163], v[118:121]
	v_mfma_f32_16x16x32_bf16 v[114:117], v[144:147], v[160:163], v[114:117]
	v_mfma_f32_16x16x32_bf16 v[110:113], v[134:137], v[168:171], v[110:113]
	v_mfma_f32_16x16x32_bf16 v[106:109], v[144:147], v[168:171], v[106:109]
	v_mfma_f32_16x16x32_bf16 v[102:105], v[134:137], v[176:179], v[102:105]
	v_mfma_f32_16x16x32_bf16 v[98:101], v[144:147], v[176:179], v[98:101]
	v_mfma_f32_16x16x32_bf16 v[126:129], v[138:141], v[156:159], v[126:129]
	v_mfma_f32_16x16x32_bf16 v[122:125], v[148:151], v[156:159], v[122:125]
	v_mfma_f32_16x16x32_bf16 v[118:121], v[138:141], v[164:167], v[118:121]
	v_mfma_f32_16x16x32_bf16 v[114:117], v[148:151], v[164:167], v[114:117]
	v_mfma_f32_16x16x32_bf16 v[110:113], v[138:141], v[172:175], v[110:113]
	v_mfma_f32_16x16x32_bf16 v[106:109], v[148:151], v[172:175], v[106:109]
	v_mfma_f32_16x16x32_bf16 v[102:105], v[138:141], v[180:183], v[102:105]
	v_mfma_f32_16x16x32_bf16 v[98:101], v[148:151], v[180:183], v[98:101]
	s_setprio 0
	v_add_u32_e32 v192, 0x14000, v143
	s_barrier
	ds_read_b128 v[130:133], v192
	ds_read_b128 v[184:187], v192 offset:1024
	ds_read_b128 v[188:191], v192 offset:2048
	ds_read_b128 v[192:195], v192 offset:3072
	s_barrier
	s_waitcnt lgkmcnt(0)
	s_setprio 1
	s_waitcnt lgkmcnt(0)
	v_mfma_f32_16x16x32_bf16 v[94:97], v[130:133], v[152:155], v[94:97]
	v_mfma_f32_16x16x32_bf16 v[90:93], v[188:191], v[152:155], v[90:93]
	v_mfma_f32_16x16x32_bf16 v[78:81], v[130:133], v[160:163], v[78:81]
	v_mfma_f32_16x16x32_bf16 v[94:97], v[184:187], v[156:159], v[94:97]
	v_mfma_f32_16x16x32_bf16 v[90:93], v[192:195], v[156:159], v[90:93]
	v_mfma_f32_16x16x32_bf16 v[78:81], v[184:187], v[164:167], v[78:81]
	v_mfma_f32_16x16x32_bf16 v[62:65], v[188:191], v[160:163], v[62:65]
	v_mfma_f32_16x16x32_bf16 v[58:61], v[130:133], v[168:171], v[58:61]
	v_mfma_f32_16x16x32_bf16 v[54:57], v[188:191], v[168:171], v[54:57]
	v_mfma_f32_16x16x32_bf16 v[50:53], v[130:133], v[176:179], v[50:53]
	v_mfma_f32_16x16x32_bf16 v[46:49], v[188:191], v[176:179], v[46:49]
	v_mfma_f32_16x16x32_bf16 v[62:65], v[192:195], v[164:167], v[62:65]
	v_mfma_f32_16x16x32_bf16 v[58:61], v[184:187], v[172:175], v[58:61]
	v_mfma_f32_16x16x32_bf16 v[54:57], v[192:195], v[172:175], v[54:57]
	v_mfma_f32_16x16x32_bf16 v[50:53], v[184:187], v[180:183], v[50:53]
	v_mfma_f32_16x16x32_bf16 v[46:49], v[192:195], v[180:183], v[46:49]
	s_setprio 0
	s_barrier
	ds_read_b128 v[152:155], v142 offset:16384
	ds_read_b128 v[156:159], v142 offset:17408
	ds_read_b128 v[160:163], v142 offset:18432
	ds_read_b128 v[164:167], v142 offset:19456
	ds_read_b128 v[168:171], v142 offset:20480
	ds_read_b128 v[172:175], v142 offset:21504
	ds_read_b128 v[176:179], v142 offset:22528
	ds_read_b128 v[180:183], v142 offset:23552
	s_waitcnt vmcnt(4)
	s_barrier
	s_waitcnt lgkmcnt(0)
	s_setprio 1
	s_waitcnt lgkmcnt(0)
	v_mfma_f32_16x16x32_bf16 v[42:45], v[134:137], v[152:155], v[42:45]
	v_mfma_f32_16x16x32_bf16 v[38:41], v[144:147], v[152:155], v[38:41]
	v_mfma_f32_16x16x32_bf16 v[34:37], v[134:137], v[160:163], v[34:37]
	v_mfma_f32_16x16x32_bf16 v[30:33], v[144:147], v[160:163], v[30:33]
	v_mfma_f32_16x16x32_bf16 v[26:29], v[134:137], v[168:171], v[26:29]
	v_mfma_f32_16x16x32_bf16 v[22:25], v[144:147], v[168:171], v[22:25]
	v_mfma_f32_16x16x32_bf16 v[18:21], v[134:137], v[176:179], v[18:21]
	v_mfma_f32_16x16x32_bf16 v[14:17], v[144:147], v[176:179], v[14:17]
	v_mfma_f32_16x16x32_bf16 v[42:45], v[138:141], v[156:159], v[42:45]
	v_mfma_f32_16x16x32_bf16 v[38:41], v[148:151], v[156:159], v[38:41]
	v_mfma_f32_16x16x32_bf16 v[34:37], v[138:141], v[164:167], v[34:37]
	v_mfma_f32_16x16x32_bf16 v[30:33], v[148:151], v[164:167], v[30:33]
	v_mfma_f32_16x16x32_bf16 v[26:29], v[138:141], v[172:175], v[26:29]
	v_mfma_f32_16x16x32_bf16 v[22:25], v[148:151], v[172:175], v[22:25]
	v_mfma_f32_16x16x32_bf16 v[18:21], v[138:141], v[180:183], v[18:21]
	v_mfma_f32_16x16x32_bf16 v[14:17], v[148:151], v[180:183], v[14:17]
	s_setprio 0
	s_setprio 1
	v_mfma_f32_16x16x32_bf16 v[70:73], v[130:133], v[168:171], v[70:73]
	v_mfma_f32_16x16x32_bf16 v[198:201], v[184:187], v[172:175], v[70:73]
	v_mfma_f32_16x16x32_bf16 v[70:73], v[188:191], v[168:171], v[74:77]
	v_mfma_f32_16x16x32_bf16 v[66:69], v[188:191], v[160:163], v[66:69]
	v_mfma_f32_16x16x32_bf16 v[74:77], v[192:195], v[172:175], v[70:73]
	v_mfma_f32_16x16x32_bf16 v[70:73], v[130:133], v[176:179], v[82:85]
	v_mfma_f32_16x16x32_bf16 v[10:13], v[130:133], v[152:155], v[10:13]
	v_mfma_f32_16x16x32_bf16 v[6:9], v[188:191], v[152:155], v[6:9]
	v_mfma_f32_16x16x32_bf16 v[2:5], v[130:133], v[160:163], v[2:5]
	v_mfma_f32_16x16x32_bf16 v[66:69], v[192:195], v[164:167], v[66:69]
	v_mfma_f32_16x16x32_bf16 v[202:205], v[184:187], v[180:183], v[70:73]
	v_mfma_f32_16x16x32_bf16 v[70:73], v[188:191], v[176:179], v[86:89]
	v_mfma_f32_16x16x32_bf16 v[10:13], v[184:187], v[156:159], v[10:13]
	v_mfma_f32_16x16x32_bf16 v[6:9], v[192:195], v[156:159], v[6:9]
	v_mfma_f32_16x16x32_bf16 v[2:5], v[184:187], v[164:167], v[2:5]
	v_mfma_f32_16x16x32_bf16 v[206:209], v[192:195], v[180:183], v[70:73]
	s_setprio 0
	v_add_u32_e32 v86, 0x18000, v143
	s_barrier
	s_nop 0
	ds_read_b128 v[70:73], v86
	ds_read_b128 v[82:85], v86 offset:1024
	ds_read_b128 v[134:137], v86 offset:2048
	ds_read_b128 v[210:213], v86 offset:3072
	ds_read_b128 v[86:89], v142 offset:32768
	ds_read_b128 v[130:133], v142 offset:33792
	ds_read_b128 v[138:141], v142 offset:34816
	ds_read_b128 v[154:157], v142 offset:35840
	ds_read_b128 v[214:217], v142 offset:36864
	ds_read_b128 v[218:221], v142 offset:37888
	ds_read_b128 v[226:229], v142 offset:38912
	ds_read_b128 v[230:233], v142 offset:39936
	s_waitcnt vmcnt(2)
	s_barrier
	s_waitcnt lgkmcnt(0)
	s_setprio 1
	s_waitcnt lgkmcnt(0)
	v_mfma_f32_16x16x32_bf16 v[126:129], v[70:73], v[86:89], v[126:129]
	v_mfma_f32_16x16x32_bf16 v[122:125], v[134:137], v[86:89], v[122:125]
	v_mfma_f32_16x16x32_bf16 v[118:121], v[70:73], v[138:141], v[118:121]
	v_mfma_f32_16x16x32_bf16 v[114:117], v[134:137], v[138:141], v[114:117]
	v_mfma_f32_16x16x32_bf16 v[110:113], v[70:73], v[214:217], v[110:113]
	v_mfma_f32_16x16x32_bf16 v[106:109], v[134:137], v[214:217], v[106:109]
	v_mfma_f32_16x16x32_bf16 v[102:105], v[70:73], v[226:229], v[102:105]
	v_mfma_f32_16x16x32_bf16 v[98:101], v[134:137], v[226:229], v[98:101]
	v_mfma_f32_16x16x32_bf16 v[182:185], v[82:85], v[130:133], v[126:129]
	v_mfma_f32_16x16x32_bf16 v[178:181], v[210:213], v[130:133], v[122:125]
	v_mfma_f32_16x16x32_bf16 v[166:169], v[82:85], v[154:157], v[118:121]
	v_mfma_f32_16x16x32_bf16 v[162:165], v[210:213], v[154:157], v[114:117]
	v_mfma_f32_16x16x32_bf16 v[150:153], v[82:85], v[218:221], v[110:113]
	v_mfma_f32_16x16x32_bf16 v[146:149], v[210:213], v[218:221], v[106:109]
	v_mfma_f32_16x16x32_bf16 v[122:125], v[82:85], v[230:233], v[102:105]
	v_mfma_f32_16x16x32_bf16 v[114:117], v[210:213], v[230:233], v[98:101]
	s_setprio 0
	s_nop 1
	v_add_u32_e32 v98, 0x1c000, v143
	s_barrier
	ds_read_b128 v[234:237], v98
	ds_read_b128 v[238:241], v98 offset:1024
	ds_read_b128 v[242:245], v98 offset:2048
	ds_read_b128 v[246:249], v98 offset:3072
	s_waitcnt vmcnt(0)
	s_barrier
	s_waitcnt lgkmcnt(0)
	s_setprio 1
	s_waitcnt lgkmcnt(0)
	v_mfma_f32_16x16x32_bf16 v[94:97], v[234:237], v[86:89], v[94:97]
	v_mfma_f32_16x16x32_bf16 v[86:89], v[242:245], v[86:89], v[90:93]
	v_mfma_f32_16x16x32_bf16 v[78:81], v[234:237], v[138:141], v[78:81]
	v_mfma_f32_16x16x32_bf16 v[62:65], v[242:245], v[138:141], v[62:65]
	v_mfma_f32_16x16x32_bf16 v[58:61], v[234:237], v[214:217], v[58:61]
	v_mfma_f32_16x16x32_bf16 v[54:57], v[242:245], v[214:217], v[54:57]
	v_mfma_f32_16x16x32_bf16 v[50:53], v[234:237], v[226:229], v[50:53]
	v_mfma_f32_16x16x32_bf16 v[46:49], v[242:245], v[226:229], v[46:49]
	v_mfma_f32_16x16x32_bf16 v[190:193], v[238:241], v[130:133], v[94:97]
	v_mfma_f32_16x16x32_bf16 v[186:189], v[246:249], v[130:133], v[86:89]
	v_mfma_f32_16x16x32_bf16 v[174:177], v[238:241], v[154:157], v[78:81]
	v_mfma_f32_16x16x32_bf16 v[170:173], v[246:249], v[154:157], v[62:65]
	v_mfma_f32_16x16x32_bf16 v[158:161], v[238:241], v[218:221], v[58:61]
	v_mfma_f32_16x16x32_bf16 v[154:157], v[246:249], v[218:221], v[54:57]
	v_mfma_f32_16x16x32_bf16 v[138:141], v[238:241], v[230:233], v[50:53]
	v_mfma_f32_16x16x32_bf16 v[130:133], v[246:249], v[230:233], v[46:49]
	s_setprio 0
	s_barrier
	s_nop 0
	ds_read_b128 v[46:49], v142 offset:49152
	ds_read_b128 v[50:53], v142 offset:50176
	ds_read_b128 v[54:57], v142 offset:51200
	ds_read_b128 v[58:61], v142 offset:52224
	ds_read_b128 v[62:65], v142 offset:53248
	ds_read_b128 v[214:217], v142 offset:54272
	ds_read_b128 v[218:221], v142 offset:55296
	ds_read_b128 v[226:229], v142 offset:56320
	s_barrier
	s_waitcnt lgkmcnt(0)
	s_setprio 1
	s_waitcnt lgkmcnt(0)
	v_mfma_f32_16x16x32_bf16 v[42:45], v[70:73], v[46:49], v[42:45]
	v_mfma_f32_16x16x32_bf16 v[38:41], v[134:137], v[46:49], v[38:41]
	v_mfma_f32_16x16x32_bf16 v[34:37], v[70:73], v[54:57], v[34:37]
	v_mfma_f32_16x16x32_bf16 v[30:33], v[134:137], v[54:57], v[30:33]
	v_mfma_f32_16x16x32_bf16 v[26:29], v[70:73], v[62:65], v[26:29]
	v_mfma_f32_16x16x32_bf16 v[22:25], v[134:137], v[62:65], v[22:25]
	v_mfma_f32_16x16x32_bf16 v[18:21], v[70:73], v[218:221], v[18:21]
	v_mfma_f32_16x16x32_bf16 v[14:17], v[134:137], v[218:221], v[14:17]
	v_mfma_f32_16x16x32_bf16 v[142:145], v[82:85], v[50:53], v[42:45]
	v_mfma_f32_16x16x32_bf16 v[126:129], v[210:213], v[50:53], v[38:41]
	v_mfma_f32_16x16x32_bf16 v[110:113], v[82:85], v[58:61], v[34:37]
	v_mfma_f32_16x16x32_bf16 v[102:105], v[210:213], v[58:61], v[30:33]
	v_mfma_f32_16x16x32_bf16 v[94:97], v[82:85], v[214:217], v[26:29]
	v_mfma_f32_16x16x32_bf16 v[86:89], v[210:213], v[214:217], v[22:25]
	v_mfma_f32_16x16x32_bf16 v[78:81], v[82:85], v[226:229], v[18:21]
	v_mfma_f32_16x16x32_bf16 v[70:73], v[210:213], v[226:229], v[14:17]
	s_setprio 0
	s_setprio 1
	v_mfma_f32_16x16x32_bf16 v[2:5], v[234:237], v[54:57], v[2:5]
	v_mfma_f32_16x16x32_bf16 v[106:109], v[238:241], v[58:61], v[2:5]
	v_mfma_f32_16x16x32_bf16 v[2:5], v[242:245], v[54:57], v[66:69]
	v_mfma_f32_16x16x32_bf16 v[98:101], v[246:249], v[58:61], v[2:5]
	v_mfma_f32_16x16x32_bf16 v[2:5], v[234:237], v[62:65], v[198:201]
	v_mfma_f32_16x16x32_bf16 v[90:93], v[238:241], v[214:217], v[2:5]
	v_mfma_f32_16x16x32_bf16 v[2:5], v[242:245], v[62:65], v[74:77]
	v_mfma_f32_16x16x32_bf16 v[82:85], v[246:249], v[214:217], v[2:5]
	v_mfma_f32_16x16x32_bf16 v[2:5], v[234:237], v[218:221], v[202:205]
	v_mfma_f32_16x16x32_bf16 v[10:13], v[234:237], v[46:49], v[10:13]
	v_mfma_f32_16x16x32_bf16 v[6:9], v[242:245], v[46:49], v[6:9]
	v_mfma_f32_16x16x32_bf16 v[74:77], v[238:241], v[226:229], v[2:5]
	v_mfma_f32_16x16x32_bf16 v[2:5], v[242:245], v[218:221], v[206:209]
	v_mfma_f32_16x16x32_bf16 v[134:137], v[238:241], v[50:53], v[10:13]
	v_mfma_f32_16x16x32_bf16 v[118:121], v[246:249], v[50:53], v[6:9]
	v_mfma_f32_16x16x32_bf16 v[66:69], v[246:249], v[226:229], v[2:5]
	s_setprio 0
	s_cmpk_lt_u32 s33, 0x100
	s_barrier
	s_cbranch_scc0 .LBB0_164
	s_barrier

.LBB0_195:
	v_and_b32_e32 v17, 15, v16
	v_and_b32_e32 v18, 48, v16
	v_lshlrev_b32_e32 v16, 2, v16
	v_lshlrev_b32_e32 v17, 6, v17
	v_and_b32_e32 v16, 32, v16
	s_lshl_b32 s37, s37, 12
	v_or_b32_e32 v19, v17, v18
	v_bitop3_b32 v17, v17, v16, v18 bitop3:0x36
	s_lshl_b32 s36, s36, 13
	s_and_b32 s37, s37, 0x3000
	s_add_i32 m0, s69, 0x18000
	v_lshl_add_u64 v[8:9], v[8:9], 0, s[48:49]
	v_bitop3_b32 v16, v19, s36, v16 bitop3:0xde
	v_or_b32_e32 v143, s37, v17
	s_waitcnt vmcnt(2)
	s_barrier
	global_load_lds_dwordx4 v[8:9], off
	v_lshl_add_u64 v[6:7], v[6:7], 0, s[48:49]
	s_add_i32 m0, s69, 0x1a000
	s_add_i32 s36, s69, 0x8000
	s_add_i32 s37, s69, 0xa000
	global_load_lds_dwordx4 v[6:7], off
	v_lshl_add_u64 v[4:5], v[4:5], 0, s[48:49]
	s_mov_b32 m0, s36
	s_add_u32 s76, vcc_lo, 0x40080
	global_load_lds_dwordx4 v[4:5], off
	v_lshl_add_u64 v[2:3], v[2:3], 0, s[48:49]
	s_mov_b32 m0, s37
	s_addc_u32 s77, vcc_hi, 0
	global_load_lds_dwordx4 v[2:3], off
	s_add_i32 m0, s69, 0x1c000
	v_lshl_add_u64 v[2:3], s[76:77], 0, v[130:131]
	global_load_lds_dwordx4 v[2:3], off
	v_lshl_add_u64 v[2:3], s[76:77], 0, v[132:133]
	s_add_i32 m0, s69, 0x1e000
	v_readlane_b32 s18, v253, 1
	global_load_lds_dwordx4 v[2:3], off
	v_lshlrev_b32_e32 v2, 14, v10
	v_and_b32_e32 v2, 0xffff8000, v2
	v_readlane_b32 s19, v253, 2
	s_add_u32 s44, s18, s44
	v_lshlrev_b32_e32 v4, 14, v11
	v_lshl_add_u32 v2, v12, 11, v2
	v_and_b32_e32 v3, 1, v10
	s_addc_u32 s45, s19, s45
	v_and_b32_e32 v4, 0xffff8000, v4
	v_lshl_or_b32 v2, v3, 6, v2
	v_lshl_add_u32 v4, v14, 11, v4
	v_and_b32_e32 v5, 1, v11
	s_add_u32 s40, s18, s40
	s_waitcnt vmcnt(6)
	v_lshl_add_u32 v2, v13, 1, v2
	v_mov_b32_e32 v3, v196
	v_lshl_or_b32 v4, v5, 6, v4
	s_addc_u32 s41, s19, s41
	v_lshl_add_u64 v[134:135], s[44:45], 0, v[2:3]
	v_lshl_add_u32 v4, v15, 1, v4
	v_mov_b32_e32 v5, v196
	v_lshl_add_u64 v[138:139], s[40:41], 0, v[2:3]
	v_mov_b32_e32 v2, 0
	v_lshl_add_u64 v[136:137], s[44:45], 0, v[4:5]
	v_lshl_add_u64 v[140:141], s[40:41], 0, v[4:5]
	s_mov_b32 s40, -2
	v_add_u32_e32 v142, 0, v16
	v_mov_b32_e32 v3, v2
	v_mov_b32_e32 v4, v2
	v_mov_b32_e32 v5, v2
	v_mov_b32_e32 v6, v2
	v_mov_b32_e32 v7, v2
	v_mov_b32_e32 v8, v2
	v_mov_b32_e32 v9, v2
	v_mov_b32_e32 v10, v2
	v_mov_b32_e32 v11, v2
	v_mov_b32_e32 v12, v2
	v_mov_b32_e32 v13, v2
	v_mov_b32_e32 v14, v2
	v_mov_b32_e32 v15, v2
	v_mov_b32_e32 v16, v2
	v_mov_b32_e32 v17, v2
	v_mov_b32_e32 v18, v2
	v_mov_b32_e32 v19, v2
	v_mov_b32_e32 v20, v2
	v_mov_b32_e32 v21, v2
	v_mov_b32_e32 v22, v2
	v_mov_b32_e32 v23, v2
	v_mov_b32_e32 v24, v2
	v_mov_b32_e32 v25, v2
	v_mov_b32_e32 v26, v2
	v_mov_b32_e32 v27, v2
	v_mov_b32_e32 v28, v2
	v_mov_b32_e32 v29, v2
	v_mov_b32_e32 v30, v2
	v_mov_b32_e32 v31, v2
	v_mov_b32_e32 v32, v2
	v_mov_b32_e32 v33, v2
	v_mov_b32_e32 v34, v2
	v_mov_b32_e32 v35, v2
	v_mov_b32_e32 v36, v2
	v_mov_b32_e32 v37, v2
	v_mov_b32_e32 v38, v2
	v_mov_b32_e32 v39, v2
	v_mov_b32_e32 v40, v2
	v_mov_b32_e32 v41, v2
	v_mov_b32_e32 v42, v2
	v_mov_b32_e32 v43, v2
	v_mov_b32_e32 v44, v2
	v_mov_b32_e32 v45, v2
	v_mov_b32_e32 v46, v2
	v_mov_b32_e32 v47, v2
	v_mov_b32_e32 v48, v2
	v_mov_b32_e32 v49, v2
	v_mov_b32_e32 v50, v2
	v_mov_b32_e32 v51, v2
	v_mov_b32_e32 v52, v2
	v_mov_b32_e32 v53, v2
	v_mov_b32_e32 v54, v2
	v_mov_b32_e32 v55, v2
	v_mov_b32_e32 v56, v2
	v_mov_b32_e32 v57, v2
	v_mov_b32_e32 v58, v2
	v_mov_b32_e32 v59, v2
	v_mov_b32_e32 v60, v2
	v_mov_b32_e32 v61, v2
	v_mov_b32_e32 v62, v2
	v_mov_b32_e32 v63, v2
	v_mov_b32_e32 v64, v2
	v_mov_b32_e32 v65, v2
	v_mov_b32_e32 v66, v2
	v_mov_b32_e32 v67, v2
	v_mov_b32_e32 v68, v2
	v_mov_b32_e32 v69, v2
	v_mov_b32_e32 v70, v2
	v_mov_b32_e32 v71, v2
	v_mov_b32_e32 v72, v2
	v_mov_b32_e32 v73, v2
	v_mov_b32_e32 v78, v2
	v_mov_b32_e32 v79, v2
	v_mov_b32_e32 v80, v2
	v_mov_b32_e32 v81, v2
	v_mov_b32_e32 v82, v2
	v_mov_b32_e32 v83, v2
	v_mov_b32_e32 v84, v2
	v_mov_b32_e32 v85, v2
	v_mov_b32_e32 v86, v2
	v_mov_b32_e32 v87, v2
	v_mov_b32_e32 v88, v2
	v_mov_b32_e32 v89, v2
	v_mov_b32_e32 v90, v2
	v_mov_b32_e32 v91, v2
	v_mov_b32_e32 v92, v2
	v_mov_b32_e32 v93, v2
	v_mov_b32_e32 v94, v2
	v_mov_b32_e32 v95, v2
	v_mov_b32_e32 v96, v2
	v_mov_b32_e32 v97, v2
	v_mov_b32_e32 v98, v2
	v_mov_b32_e32 v99, v2
	v_mov_b32_e32 v100, v2
	v_mov_b32_e32 v101, v2
	v_mov_b32_e32 v102, v2
	v_mov_b32_e32 v103, v2
	v_mov_b32_e32 v104, v2
	v_mov_b32_e32 v105, v2
	v_mov_b32_e32 v106, v2
	v_mov_b32_e32 v107, v2
	v_mov_b32_e32 v108, v2
	v_mov_b32_e32 v109, v2
	v_mov_b32_e32 v110, v2
	v_mov_b32_e32 v111, v2
	v_mov_b32_e32 v112, v2
	v_mov_b32_e32 v113, v2
	v_mov_b32_e32 v114, v2
	v_mov_b32_e32 v115, v2
	v_mov_b32_e32 v116, v2
	v_mov_b32_e32 v117, v2
	v_mov_b32_e32 v118, v2
	v_mov_b32_e32 v119, v2
	v_mov_b32_e32 v120, v2
	v_mov_b32_e32 v121, v2
	v_mov_b32_e32 v122, v2
	v_mov_b32_e32 v123, v2
	v_mov_b32_e32 v124, v2
	v_mov_b32_e32 v125, v2
	v_mov_b32_e32 v126, v2
	v_mov_b32_e32 v127, v2
	v_mov_b32_e32 v128, v2
	v_mov_b32_e32 v129, v2
	v_mov_b32_e32 v74, v2
	v_mov_b32_e32 v75, v2
	v_mov_b32_e32 v76, v2
	v_mov_b32_e32 v77, v2
	s_barrier
.LBB0_196:
	v_add_u32_e32 v156, 0x10000, v143
	ds_read_b128 v[144:147], v156
	ds_read_b128 v[148:151], v156 offset:1024
	ds_read_b128 v[152:155], v156 offset:2048
	ds_read_b128 v[156:159], v156 offset:3072
	ds_read_b128 v[160:163], v142
	ds_read_b128 v[164:167], v142 offset:1024
	ds_read_b128 v[168:171], v142 offset:2048
	ds_read_b128 v[172:175], v142 offset:3072
	ds_read_b128 v[176:179], v142 offset:4096
	ds_read_b128 v[180:183], v142 offset:5120
	ds_read_b128 v[184:187], v142 offset:6144
	ds_read_b128 v[188:191], v142 offset:7168
	s_add_i32 s45, 0, 0x10000
	v_lshl_add_u64 v[210:211], v[138:139], 0, s[14:15]
	s_add_i32 s44, s69, 0xc000
	v_lshl_add_u64 v[192:193], v[210:211], 0, s[94:95]
	s_mov_b32 m0, s44
	v_lshl_add_u64 v[212:213], v[140:141], 0, s[14:15]
	s_add_i32 s41, s69, 0xe000
	global_load_lds_dwordx4 v[192:193], off
	v_lshl_add_u64 v[192:193], v[212:213], 0, s[94:95]
	s_mov_b32 m0, s41
	s_nop 0
	global_load_lds_dwordx4 v[192:193], off
	v_add_u32_e32 v197, 0x14000, v143
	ds_read_b128 v[192:195], v197
	ds_read_b128 v[198:201], v197 offset:1024
	ds_read_b128 v[202:205], v197 offset:2048
	ds_read_b128 v[206:209], v197 offset:3072
	s_waitcnt vmcnt(8)
	s_waitcnt lgkmcnt(0)
	s_barrier
	s_setprio 1
	v_mfma_f32_16x16x32_bf16 v[126:129], v[144:147], v[160:163], v[126:129]
	v_mfma_f32_16x16x32_bf16 v[122:125], v[152:155], v[160:163], v[122:125]
	v_mfma_f32_16x16x32_bf16 v[118:121], v[144:147], v[168:171], v[118:121]
	v_mfma_f32_16x16x32_bf16 v[114:117], v[152:155], v[168:171], v[114:117]
	v_mfma_f32_16x16x32_bf16 v[110:113], v[144:147], v[176:179], v[110:113]
	v_mfma_f32_16x16x32_bf16 v[106:109], v[152:155], v[176:179], v[106:109]
	v_mfma_f32_16x16x32_bf16 v[102:105], v[144:147], v[184:187], v[102:105]
	v_mfma_f32_16x16x32_bf16 v[98:101], v[152:155], v[184:187], v[98:101]
	v_mfma_f32_16x16x32_bf16 v[126:129], v[148:151], v[164:167], v[126:129]
	v_mfma_f32_16x16x32_bf16 v[122:125], v[156:159], v[164:167], v[122:125]
	v_mfma_f32_16x16x32_bf16 v[118:121], v[148:151], v[172:175], v[118:121]
	v_mfma_f32_16x16x32_bf16 v[114:117], v[156:159], v[172:175], v[114:117]
	v_mfma_f32_16x16x32_bf16 v[110:113], v[148:151], v[180:183], v[110:113]
	v_mfma_f32_16x16x32_bf16 v[106:109], v[156:159], v[180:183], v[106:109]
	v_mfma_f32_16x16x32_bf16 v[102:105], v[148:151], v[188:191], v[102:105]
	v_mfma_f32_16x16x32_bf16 v[98:101], v[156:159], v[188:191], v[98:101]
	v_mfma_f32_16x16x32_bf16 v[94:97], v[192:195], v[160:163], v[94:97]
	v_mfma_f32_16x16x32_bf16 v[90:93], v[202:205], v[160:163], v[90:93]
	v_mfma_f32_16x16x32_bf16 v[86:89], v[192:195], v[168:171], v[86:89]
	v_mfma_f32_16x16x32_bf16 v[82:85], v[202:205], v[168:171], v[82:85]
	v_mfma_f32_16x16x32_bf16 v[78:81], v[192:195], v[176:179], v[78:81]
	v_mfma_f32_16x16x32_bf16 v[70:73], v[202:205], v[176:179], v[70:73]
	v_mfma_f32_16x16x32_bf16 v[66:69], v[192:195], v[184:187], v[66:69]
	v_mfma_f32_16x16x32_bf16 v[62:65], v[202:205], v[184:187], v[62:65]
	v_mfma_f32_16x16x32_bf16 v[94:97], v[198:201], v[164:167], v[94:97]
	v_mfma_f32_16x16x32_bf16 v[90:93], v[206:209], v[164:167], v[90:93]
	v_mfma_f32_16x16x32_bf16 v[86:89], v[198:201], v[172:175], v[86:89]
	v_mfma_f32_16x16x32_bf16 v[82:85], v[206:209], v[172:175], v[82:85]
	v_mfma_f32_16x16x32_bf16 v[78:81], v[198:201], v[180:183], v[78:81]
	v_mfma_f32_16x16x32_bf16 v[70:73], v[206:209], v[180:183], v[70:73]
	v_mfma_f32_16x16x32_bf16 v[66:69], v[198:201], v[188:191], v[66:69]
	v_mfma_f32_16x16x32_bf16 v[62:65], v[206:209], v[188:191], v[62:65]
	s_setprio 0
	s_mov_b32 m0, s69
	v_lshl_add_u64 v[218:219], v[210:211], 0, s[38:39]
	s_barrier
	ds_read_b128 v[160:163], v142 offset:16384
	ds_read_b128 v[164:167], v142 offset:17408
	ds_read_b128 v[168:171], v142 offset:18432
	ds_read_b128 v[172:175], v142 offset:19456
	ds_read_b128 v[176:179], v142 offset:20480
	ds_read_b128 v[180:183], v142 offset:21504
	ds_read_b128 v[184:187], v142 offset:22528
	ds_read_b128 v[188:191], v142 offset:23552
	global_load_lds_dwordx4 v[218:219], off
	v_lshl_add_u64 v[218:219], v[212:213], 0, s[38:39]
	s_mov_b32 m0, s73
	s_nop 0
	global_load_lds_dwordx4 v[218:219], off
	s_add_i32 s75, 0, 0x14000
	v_lshl_add_u64 v[214:215], v[134:135], 0, s[14:15]
	s_add_i32 s45, s45, s68
	v_lshl_add_u64 v[216:217], v[214:215], 0, s[96:97]
	s_mov_b32 m0, s45
	s_nop 0
	global_load_lds_dwordx4 v[216:217], off
	v_lshl_add_u64 v[216:217], v[136:137], 0, s[14:15]
	v_lshl_add_u64 v[218:219], v[216:217], 0, s[96:97]
	s_add_i32 m0, s45, 0x2000
	s_nop 0
	global_load_lds_dwordx4 v[218:219], off
	s_add_i32 s45, s75, s68
	v_lshl_add_u64 v[218:219], v[214:215], 0, s[50:51]
	s_mov_b32 m0, s45
	s_nop 0
	global_load_lds_dwordx4 v[218:219], off
	v_lshl_add_u64 v[218:219], v[216:217], 0, s[50:51]
	s_add_i32 m0, s45, 0x2000
	s_nop 0
	global_load_lds_dwordx4 v[218:219], off
	s_waitcnt vmcnt(8)
	s_waitcnt lgkmcnt(0)
	s_barrier
	s_setprio 1
	v_mfma_f32_16x16x32_bf16 v[58:61], v[144:147], v[160:163], v[58:61]
	v_mfma_f32_16x16x32_bf16 v[54:57], v[152:155], v[160:163], v[54:57]
	v_mfma_f32_16x16x32_bf16 v[50:53], v[144:147], v[168:171], v[50:53]
	v_mfma_f32_16x16x32_bf16 v[46:49], v[152:155], v[168:171], v[46:49]
	v_mfma_f32_16x16x32_bf16 v[42:45], v[144:147], v[176:179], v[42:45]
	v_mfma_f32_16x16x32_bf16 v[38:41], v[152:155], v[176:179], v[38:41]
	v_mfma_f32_16x16x32_bf16 v[34:37], v[144:147], v[184:187], v[34:37]
	v_mfma_f32_16x16x32_bf16 v[30:33], v[152:155], v[184:187], v[30:33]
	v_mfma_f32_16x16x32_bf16 v[58:61], v[148:151], v[164:167], v[58:61]
	v_mfma_f32_16x16x32_bf16 v[54:57], v[156:159], v[164:167], v[54:57]
	v_mfma_f32_16x16x32_bf16 v[50:53], v[148:151], v[172:175], v[50:53]
	v_mfma_f32_16x16x32_bf16 v[46:49], v[156:159], v[172:175], v[46:49]
	v_mfma_f32_16x16x32_bf16 v[42:45], v[148:151], v[180:183], v[42:45]
	v_mfma_f32_16x16x32_bf16 v[38:41], v[156:159], v[180:183], v[38:41]
	v_mfma_f32_16x16x32_bf16 v[34:37], v[148:151], v[188:191], v[34:37]
	v_mfma_f32_16x16x32_bf16 v[30:33], v[156:159], v[188:191], v[30:33]
	v_mfma_f32_16x16x32_bf16 v[26:29], v[192:195], v[160:163], v[26:29]
	v_mfma_f32_16x16x32_bf16 v[22:25], v[202:205], v[160:163], v[22:25]
	v_mfma_f32_16x16x32_bf16 v[18:21], v[192:195], v[168:171], v[18:21]
	v_mfma_f32_16x16x32_bf16 v[14:17], v[202:205], v[168:171], v[14:17]
	v_mfma_f32_16x16x32_bf16 v[10:13], v[192:195], v[176:179], v[10:13]
	v_mfma_f32_16x16x32_bf16 v[6:9], v[202:205], v[176:179], v[6:9]
	v_mfma_f32_16x16x32_bf16 v[2:5], v[192:195], v[184:187], v[2:5]
	v_mfma_f32_16x16x32_bf16 v[74:77], v[202:205], v[184:187], v[74:77]
	v_mfma_f32_16x16x32_bf16 v[26:29], v[198:201], v[164:167], v[26:29]
	v_mfma_f32_16x16x32_bf16 v[22:25], v[206:209], v[164:167], v[22:25]
	v_mfma_f32_16x16x32_bf16 v[18:21], v[198:201], v[172:175], v[18:21]
	v_mfma_f32_16x16x32_bf16 v[14:17], v[206:209], v[172:175], v[14:17]
	v_mfma_f32_16x16x32_bf16 v[10:13], v[198:201], v[180:183], v[10:13]
	v_mfma_f32_16x16x32_bf16 v[6:9], v[206:209], v[180:183], v[6:9]
	v_mfma_f32_16x16x32_bf16 v[2:5], v[198:201], v[188:191], v[2:5]
	v_mfma_f32_16x16x32_bf16 v[74:77], v[206:209], v[188:191], v[74:77]
	s_setprio 0
	s_add_i32 s45, 0, 0x18000
	s_barrier
	v_add_u32_e32 v156, 0x18000, v143
	ds_read_b128 v[144:147], v156
	ds_read_b128 v[148:151], v156 offset:1024
	ds_read_b128 v[152:155], v156 offset:2048
	ds_read_b128 v[156:159], v156 offset:3072
	ds_read_b128 v[160:163], v142 offset:32768
	ds_read_b128 v[164:167], v142 offset:33792
	ds_read_b128 v[168:171], v142 offset:34816
	ds_read_b128 v[172:175], v142 offset:35840
	ds_read_b128 v[176:179], v142 offset:36864
	ds_read_b128 v[180:183], v142 offset:37888
	ds_read_b128 v[184:187], v142 offset:38912
	ds_read_b128 v[188:191], v142 offset:39936
	s_mov_b32 m0, s78
	v_lshl_add_u64 v[192:193], v[210:211], 0, s[4:5]
	global_load_lds_dwordx4 v[192:193], off
	v_lshl_add_u64 v[192:193], v[212:213], 0, s[4:5]
	s_mov_b32 m0, s74
	s_nop 0
	global_load_lds_dwordx4 v[192:193], off
	v_add_u32_e32 v197, 0x1c000, v143
	ds_read_b128 v[192:195], v197
	ds_read_b128 v[198:201], v197 offset:1024
	ds_read_b128 v[202:205], v197 offset:2048
	ds_read_b128 v[206:209], v197 offset:3072
	s_waitcnt vmcnt(8)
	s_waitcnt lgkmcnt(0)
	s_barrier
	s_setprio 1
	v_mfma_f32_16x16x32_bf16 v[126:129], v[144:147], v[160:163], v[126:129]
	v_mfma_f32_16x16x32_bf16 v[122:125], v[152:155], v[160:163], v[122:125]
	v_mfma_f32_16x16x32_bf16 v[118:121], v[144:147], v[168:171], v[118:121]
	v_mfma_f32_16x16x32_bf16 v[114:117], v[152:155], v[168:171], v[114:117]
	v_mfma_f32_16x16x32_bf16 v[110:113], v[144:147], v[176:179], v[110:113]
	v_mfma_f32_16x16x32_bf16 v[106:109], v[152:155], v[176:179], v[106:109]
	v_mfma_f32_16x16x32_bf16 v[102:105], v[144:147], v[184:187], v[102:105]
	v_mfma_f32_16x16x32_bf16 v[98:101], v[152:155], v[184:187], v[98:101]
	v_mfma_f32_16x16x32_bf16 v[126:129], v[148:151], v[164:167], v[126:129]
	v_mfma_f32_16x16x32_bf16 v[122:125], v[156:159], v[164:167], v[122:125]
	v_mfma_f32_16x16x32_bf16 v[118:121], v[148:151], v[172:175], v[118:121]
	v_mfma_f32_16x16x32_bf16 v[114:117], v[156:159], v[172:175], v[114:117]
	v_mfma_f32_16x16x32_bf16 v[110:113], v[148:151], v[180:183], v[110:113]
	v_mfma_f32_16x16x32_bf16 v[106:109], v[156:159], v[180:183], v[106:109]
	v_mfma_f32_16x16x32_bf16 v[102:105], v[148:151], v[188:191], v[102:105]
	v_mfma_f32_16x16x32_bf16 v[98:101], v[156:159], v[188:191], v[98:101]
	v_mfma_f32_16x16x32_bf16 v[94:97], v[192:195], v[160:163], v[94:97]
	v_mfma_f32_16x16x32_bf16 v[90:93], v[202:205], v[160:163], v[90:93]
	v_mfma_f32_16x16x32_bf16 v[86:89], v[192:195], v[168:171], v[86:89]
	v_mfma_f32_16x16x32_bf16 v[82:85], v[202:205], v[168:171], v[82:85]
	v_mfma_f32_16x16x32_bf16 v[78:81], v[192:195], v[176:179], v[78:81]
	v_mfma_f32_16x16x32_bf16 v[70:73], v[202:205], v[176:179], v[70:73]
	v_mfma_f32_16x16x32_bf16 v[66:69], v[192:195], v[184:187], v[66:69]
	v_mfma_f32_16x16x32_bf16 v[62:65], v[202:205], v[184:187], v[62:65]
	v_mfma_f32_16x16x32_bf16 v[94:97], v[198:201], v[164:167], v[94:97]
	v_mfma_f32_16x16x32_bf16 v[90:93], v[206:209], v[164:167], v[90:93]
	v_mfma_f32_16x16x32_bf16 v[86:89], v[198:201], v[172:175], v[86:89]
	v_mfma_f32_16x16x32_bf16 v[82:85], v[206:209], v[172:175], v[82:85]
	v_mfma_f32_16x16x32_bf16 v[78:81], v[198:201], v[180:183], v[78:81]
	v_mfma_f32_16x16x32_bf16 v[70:73], v[206:209], v[180:183], v[70:73]
	v_mfma_f32_16x16x32_bf16 v[66:69], v[198:201], v[188:191], v[66:69]
	v_mfma_f32_16x16x32_bf16 v[62:65], v[206:209], v[188:191], v[62:65]
	s_setprio 0
	s_mov_b32 m0, s36
	v_lshl_add_u64 v[210:211], v[210:211], 0, s[8:9]
	s_barrier
	ds_read_b128 v[160:163], v142 offset:49152
	ds_read_b128 v[164:167], v142 offset:50176
	ds_read_b128 v[168:171], v142 offset:51200
	ds_read_b128 v[172:175], v142 offset:52224
	ds_read_b128 v[176:179], v142 offset:53248
	ds_read_b128 v[180:183], v142 offset:54272
	ds_read_b128 v[184:187], v142 offset:55296
	ds_read_b128 v[188:191], v142 offset:56320
	global_load_lds_dwordx4 v[210:211], off
	v_lshl_add_u64 v[210:211], v[212:213], 0, s[8:9]
	s_mov_b32 m0, s37
	s_nop 0
	global_load_lds_dwordx4 v[210:211], off
	s_add_i32 s75, 0, 0x1c000
	s_add_i32 s45, s45, s68
	v_lshl_add_u64 v[218:219], v[214:215], 0, s[6:7]
	s_mov_b32 m0, s45
	s_nop 0
	global_load_lds_dwordx4 v[218:219], off
	v_lshl_add_u64 v[218:219], v[216:217], 0, s[6:7]
	s_add_i32 m0, s45, 0x2000
	s_nop 0
	global_load_lds_dwordx4 v[218:219], off
	s_add_i32 s45, s75, s68
	v_lshl_add_u64 v[218:219], v[214:215], 0, s[10:11]
	s_mov_b32 m0, s45
	s_nop 0
	global_load_lds_dwordx4 v[218:219], off
	v_lshl_add_u64 v[218:219], v[216:217], 0, s[10:11]
	s_add_i32 m0, s45, 0x2000
	s_nop 0
	global_load_lds_dwordx4 v[218:219], off
	s_waitcnt vmcnt(8)
	s_waitcnt lgkmcnt(0)
	s_barrier
	s_setprio 1
	v_mfma_f32_16x16x32_bf16 v[58:61], v[144:147], v[160:163], v[58:61]
	v_mfma_f32_16x16x32_bf16 v[54:57], v[152:155], v[160:163], v[54:57]
	v_mfma_f32_16x16x32_bf16 v[50:53], v[144:147], v[168:171], v[50:53]
	v_mfma_f32_16x16x32_bf16 v[46:49], v[152:155], v[168:171], v[46:49]
	v_mfma_f32_16x16x32_bf16 v[42:45], v[144:147], v[176:179], v[42:45]
	v_mfma_f32_16x16x32_bf16 v[38:41], v[152:155], v[176:179], v[38:41]
	v_mfma_f32_16x16x32_bf16 v[34:37], v[144:147], v[184:187], v[34:37]
	v_mfma_f32_16x16x32_bf16 v[30:33], v[152:155], v[184:187], v[30:33]
	v_mfma_f32_16x16x32_bf16 v[58:61], v[148:151], v[164:167], v[58:61]
	v_mfma_f32_16x16x32_bf16 v[54:57], v[156:159], v[164:167], v[54:57]
	v_mfma_f32_16x16x32_bf16 v[50:53], v[148:151], v[172:175], v[50:53]
	v_mfma_f32_16x16x32_bf16 v[46:49], v[156:159], v[172:175], v[46:49]
	v_mfma_f32_16x16x32_bf16 v[42:45], v[148:151], v[180:183], v[42:45]
	v_mfma_f32_16x16x32_bf16 v[38:41], v[156:159], v[180:183], v[38:41]
	v_mfma_f32_16x16x32_bf16 v[34:37], v[148:151], v[188:191], v[34:37]
	v_mfma_f32_16x16x32_bf16 v[30:33], v[156:159], v[188:191], v[30:33]
	v_mfma_f32_16x16x32_bf16 v[26:29], v[192:195], v[160:163], v[26:29]
	v_mfma_f32_16x16x32_bf16 v[22:25], v[202:205], v[160:163], v[22:25]
	v_mfma_f32_16x16x32_bf16 v[18:21], v[192:195], v[168:171], v[18:21]
	v_mfma_f32_16x16x32_bf16 v[14:17], v[202:205], v[168:171], v[14:17]
	v_mfma_f32_16x16x32_bf16 v[10:13], v[192:195], v[176:179], v[10:13]
	v_mfma_f32_16x16x32_bf16 v[6:9], v[202:205], v[176:179], v[6:9]
	v_mfma_f32_16x16x32_bf16 v[2:5], v[192:195], v[184:187], v[2:5]
	v_mfma_f32_16x16x32_bf16 v[74:77], v[202:205], v[184:187], v[74:77]
	v_mfma_f32_16x16x32_bf16 v[26:29], v[198:201], v[164:167], v[26:29]
	v_mfma_f32_16x16x32_bf16 v[22:25], v[206:209], v[164:167], v[22:25]
	v_mfma_f32_16x16x32_bf16 v[18:21], v[198:201], v[172:175], v[18:21]
	v_mfma_f32_16x16x32_bf16 v[14:17], v[206:209], v[172:175], v[14:17]
	v_mfma_f32_16x16x32_bf16 v[10:13], v[198:201], v[180:183], v[10:13]
	v_mfma_f32_16x16x32_bf16 v[6:9], v[206:209], v[180:183], v[6:9]
	v_mfma_f32_16x16x32_bf16 v[2:5], v[198:201], v[188:191], v[2:5]
	v_mfma_f32_16x16x32_bf16 v[74:77], v[206:209], v[188:191], v[74:77]
	s_setprio 0
	s_add_i32 s40, s40, 2
	v_lshl_add_u64 v[134:135], v[134:135], 0, s[98:99]
	v_lshl_add_u64 v[136:137], v[136:137], 0, s[98:99]
	v_lshl_add_u64 v[138:139], v[138:139], 0, s[98:99]
	s_cmp_gt_u32 s40, 11
	v_lshl_add_u64 v[140:141], v[140:141], 0, s[98:99]
	s_barrier
	s_cbranch_scc0 .LBB0_196
	s_add_u32 s16, s16, 0x40780
	v_add_u32_e32 v143, 0, v143
	s_addc_u32 s17, s17, 0
	s_mov_b32 m0, s44
	v_add_u32_e32 v148, 0x10000, v143
	v_lshl_add_u64 v[130:131], s[16:17], 0, v[130:131]
	ds_read_b128 v[134:137], v148
	ds_read_b128 v[138:141], v148 offset:1024
	ds_read_b128 v[144:147], v148 offset:2048
	ds_read_b128 v[148:151], v148 offset:3072
	ds_read_b128 v[152:155], v142
	ds_read_b128 v[156:159], v142 offset:1024
	ds_read_b128 v[160:163], v142 offset:2048
	ds_read_b128 v[164:167], v142 offset:3072
	ds_read_b128 v[168:171], v142 offset:4096
	ds_read_b128 v[172:175], v142 offset:5120
	ds_read_b128 v[176:179], v142 offset:6144
	ds_read_b128 v[180:183], v142 offset:7168
	global_load_lds_dwordx4 v[130:131], off
	v_lshl_add_u64 v[130:131], s[16:17], 0, v[132:133]
	s_mov_b32 m0, s41
	s_nop 0
	global_load_lds_dwordx4 v[130:131], off
	s_barrier
	s_waitcnt lgkmcnt(0)
	s_setprio 1
	s_waitcnt lgkmcnt(0)
	v_mfma_f32_16x16x32_bf16 v[126:129], v[134:137], v[152:155], v[126:129]
	v_mfma_f32_16x16x32_bf16 v[122:125], v[144:147], v[152:155], v[122:125]
	v_mfma_f32_16x16x32_bf16 v[118:121], v[134:137], v[160:163], v[118:121]
	v_mfma_f32_16x16x32_bf16 v[114:117], v[144:147], v[160:163], v[114:117]
	v_mfma_f32_16x16x32_bf16 v[110:113], v[134:137], v[168:171], v[110:113]
	v_mfma_f32_16x16x32_bf16 v[106:109], v[144:147], v[168:171], v[106:109]
	v_mfma_f32_16x16x32_bf16 v[102:105], v[134:137], v[176:179], v[102:105]
	v_mfma_f32_16x16x32_bf16 v[126:129], v[138:141], v[156:159], v[126:129]
	v_mfma_f32_16x16x32_bf16 v[122:125], v[148:151], v[156:159], v[122:125]
	v_mfma_f32_16x16x32_bf16 v[118:121], v[138:141], v[164:167], v[118:121]
	v_mfma_f32_16x16x32_bf16 v[114:117], v[148:151], v[164:167], v[114:117]
	v_mfma_f32_16x16x32_bf16 v[110:113], v[138:141], v[172:175], v[110:113]
	v_mfma_f32_16x16x32_bf16 v[106:109], v[148:151], v[172:175], v[106:109]
	v_mfma_f32_16x16x32_bf16 v[102:105], v[138:141], v[180:183], v[102:105]
	v_mfma_f32_16x16x32_bf16 v[98:101], v[144:147], v[176:179], v[98:101]
	v_mfma_f32_16x16x32_bf16 v[98:101], v[148:151], v[180:183], v[98:101]
	s_setprio 0
	v_add_u32_e32 v192, 0x14000, v143
	s_barrier
	ds_read_b128 v[130:133], v192
	ds_read_b128 v[184:187], v192 offset:1024
	ds_read_b128 v[188:191], v192 offset:2048
	ds_read_b128 v[192:195], v192 offset:3072
	s_barrier
	s_waitcnt lgkmcnt(0)
	s_setprio 1
	s_waitcnt lgkmcnt(0)
	v_mfma_f32_16x16x32_bf16 v[94:97], v[130:133], v[152:155], v[94:97]
	v_mfma_f32_16x16x32_bf16 v[90:93], v[188:191], v[152:155], v[90:93]
	v_mfma_f32_16x16x32_bf16 v[82:85], v[188:191], v[160:163], v[82:85]
	v_mfma_f32_16x16x32_bf16 v[70:73], v[188:191], v[168:171], v[70:73]
	v_mfma_f32_16x16x32_bf16 v[66:69], v[130:133], v[176:179], v[66:69]
	v_mfma_f32_16x16x32_bf16 v[94:97], v[184:187], v[156:159], v[94:97]
	v_mfma_f32_16x16x32_bf16 v[90:93], v[192:195], v[156:159], v[90:93]
	v_mfma_f32_16x16x32_bf16 v[86:89], v[130:133], v[160:163], v[86:89]
	v_mfma_f32_16x16x32_bf16 v[82:85], v[192:195], v[164:167], v[82:85]
	v_mfma_f32_16x16x32_bf16 v[78:81], v[130:133], v[168:171], v[78:81]
	v_mfma_f32_16x16x32_bf16 v[152:155], v[192:195], v[172:175], v[70:73]
	v_mfma_f32_16x16x32_bf16 v[156:159], v[184:187], v[180:183], v[66:69]
	v_mfma_f32_16x16x32_bf16 v[62:65], v[188:191], v[176:179], v[62:65]
	v_mfma_f32_16x16x32_bf16 v[86:89], v[184:187], v[164:167], v[86:89]
	v_mfma_f32_16x16x32_bf16 v[78:81], v[184:187], v[172:175], v[78:81]
	v_mfma_f32_16x16x32_bf16 v[160:163], v[192:195], v[180:183], v[62:65]
	s_setprio 0
	s_barrier
	s_nop 2
	ds_read_b128 v[62:65], v142 offset:16384
	ds_read_b128 v[66:69], v142 offset:17408
	ds_read_b128 v[70:73], v142 offset:18432
	ds_read_b128 v[164:167], v142 offset:19456
	ds_read_b128 v[168:171], v142 offset:20480
	ds_read_b128 v[172:175], v142 offset:21504
	ds_read_b128 v[176:179], v142 offset:22528
	ds_read_b128 v[180:183], v142 offset:23552
	s_waitcnt vmcnt(4)
	s_barrier
	s_waitcnt lgkmcnt(0)
	s_setprio 1
	s_waitcnt lgkmcnt(0)
	v_mfma_f32_16x16x32_bf16 v[58:61], v[134:137], v[62:65], v[58:61]
	v_mfma_f32_16x16x32_bf16 v[50:53], v[134:137], v[70:73], v[50:53]
	v_mfma_f32_16x16x32_bf16 v[42:45], v[134:137], v[168:171], v[42:45]
	v_mfma_f32_16x16x32_bf16 v[34:37], v[134:137], v[176:179], v[34:37]
	v_mfma_f32_16x16x32_bf16 v[30:33], v[144:147], v[176:179], v[30:33]
	v_mfma_f32_16x16x32_bf16 v[202:205], v[138:141], v[66:69], v[58:61]
	v_mfma_f32_16x16x32_bf16 v[54:57], v[144:147], v[62:65], v[54:57]
	v_mfma_f32_16x16x32_bf16 v[50:53], v[138:141], v[164:167], v[50:53]
	v_mfma_f32_16x16x32_bf16 v[46:49], v[144:147], v[70:73], v[46:49]
	v_mfma_f32_16x16x32_bf16 v[214:217], v[138:141], v[172:175], v[42:45]
	v_mfma_f32_16x16x32_bf16 v[38:41], v[144:147], v[168:171], v[38:41]
	v_mfma_f32_16x16x32_bf16 v[138:141], v[138:141], v[180:183], v[34:37]
	v_mfma_f32_16x16x32_bf16 v[144:147], v[148:151], v[180:183], v[30:33]
	v_mfma_f32_16x16x32_bf16 v[206:209], v[148:151], v[66:69], v[54:57]
	v_mfma_f32_16x16x32_bf16 v[210:213], v[148:151], v[164:167], v[46:49]
	v_mfma_f32_16x16x32_bf16 v[218:221], v[148:151], v[172:175], v[38:41]
	s_setprio 0
	s_setprio 1
	v_mfma_f32_16x16x32_bf16 v[26:29], v[130:133], v[62:65], v[26:29]
	v_mfma_f32_16x16x32_bf16 v[10:13], v[130:133], v[168:171], v[10:13]
	v_mfma_f32_16x16x32_bf16 v[6:9], v[188:191], v[168:171], v[6:9]
	v_mfma_f32_16x16x32_bf16 v[2:5], v[130:133], v[176:179], v[2:5]
	v_mfma_f32_16x16x32_bf16 v[148:151], v[184:187], v[66:69], v[26:29]
	v_mfma_f32_16x16x32_bf16 v[22:25], v[188:191], v[62:65], v[22:25]
	v_mfma_f32_16x16x32_bf16 v[18:21], v[130:133], v[70:73], v[18:21]
	v_mfma_f32_16x16x32_bf16 v[14:17], v[188:191], v[70:73], v[14:17]
	v_mfma_f32_16x16x32_bf16 v[238:241], v[184:187], v[172:175], v[10:13]
	v_mfma_f32_16x16x32_bf16 v[168:171], v[192:195], v[172:175], v[6:9]
	v_mfma_f32_16x16x32_bf16 v[172:175], v[184:187], v[180:183], v[2:5]
	v_mfma_f32_16x16x32_bf16 v[2:5], v[188:191], v[176:179], v[74:77]
	v_mfma_f32_16x16x32_bf16 v[230:233], v[192:195], v[66:69], v[22:25]
	v_mfma_f32_16x16x32_bf16 v[234:237], v[184:187], v[164:167], v[18:21]
	v_mfma_f32_16x16x32_bf16 v[164:167], v[192:195], v[164:167], v[14:17]
	v_mfma_f32_16x16x32_bf16 v[176:179], v[192:195], v[180:183], v[2:5]
	s_setprio 0
	v_add_u32_e32 v6, 0x18000, v143
	s_barrier
	s_nop 0
	ds_read_b128 v[2:5], v6
	ds_read_b128 v[72:75], v6 offset:1024
	ds_read_b128 v[180:183], v6 offset:2048
	ds_read_b128 v[184:187], v6 offset:3072
	ds_read_b128 v[6:9], v142 offset:32768
	ds_read_b128 v[14:17], v142 offset:33792
	ds_read_b128 v[18:21], v142 offset:34816
	ds_read_b128 v[28:31], v142 offset:35840
	ds_read_b128 v[188:191], v142 offset:36864
	ds_read_b128 v[192:195], v142 offset:37888
	ds_read_b128 v[242:245], v142 offset:38912
	ds_read_b128 v[246:249], v142 offset:39936
	s_waitcnt vmcnt(2)
	s_barrier
	s_waitcnt lgkmcnt(0)
	s_setprio 1
	s_waitcnt lgkmcnt(0)
	v_mfma_f32_16x16x32_bf16 v[10:13], v[2:5], v[6:9], v[126:129]
	v_mfma_f32_16x16x32_bf16 v[56:59], v[72:75], v[14:17], v[10:13]
	v_mfma_f32_16x16x32_bf16 v[10:13], v[180:183], v[6:9], v[122:125]
	v_mfma_f32_16x16x32_bf16 v[68:71], v[184:187], v[14:17], v[10:13]
	v_mfma_f32_16x16x32_bf16 v[10:13], v[2:5], v[18:21], v[118:121]
	v_mfma_f32_16x16x32_bf16 v[38:41], v[72:75], v[28:31], v[10:13]
	v_mfma_f32_16x16x32_bf16 v[10:13], v[180:183], v[18:21], v[114:117]
	v_mfma_f32_16x16x32_bf16 v[60:63], v[184:187], v[28:31], v[10:13]
	v_mfma_f32_16x16x32_bf16 v[10:13], v[2:5], v[188:191], v[110:113]
	v_mfma_f32_16x16x32_bf16 v[24:27], v[72:75], v[192:195], v[10:13]
	v_mfma_f32_16x16x32_bf16 v[10:13], v[180:183], v[188:191], v[106:109]
	v_mfma_f32_16x16x32_bf16 v[42:45], v[184:187], v[192:195], v[10:13]
	v_mfma_f32_16x16x32_bf16 v[10:13], v[2:5], v[242:245], v[102:105]
	v_mfma_f32_16x16x32_bf16 v[32:35], v[180:183], v[242:245], v[98:101]
	v_mfma_f32_16x16x32_bf16 v[10:13], v[72:75], v[246:249], v[10:13]
	v_mfma_f32_16x16x32_bf16 v[34:37], v[184:187], v[246:249], v[32:35]
	s_setprio 0
	v_add_u32_e32 v22, 0x1c000, v143
	s_barrier
	ds_read_b128 v[98:101], v22
	ds_read_b128 v[102:105], v22 offset:1024
	ds_read_b128 v[226:229], v22 offset:2048
	ds_read_b128 v[198:201], v22 offset:3072
	s_waitcnt vmcnt(0)
	s_barrier
	s_waitcnt lgkmcnt(0)
	s_setprio 1
	s_waitcnt lgkmcnt(0)
	v_mfma_f32_16x16x32_bf16 v[46:49], v[98:101], v[6:9], v[94:97]
	v_mfma_f32_16x16x32_bf16 v[6:9], v[226:229], v[6:9], v[90:93]
	v_mfma_f32_16x16x32_bf16 v[130:133], v[198:201], v[14:17], v[6:9]
	v_mfma_f32_16x16x32_bf16 v[6:9], v[98:101], v[18:21], v[86:89]
	v_mfma_f32_16x16x32_bf16 v[64:67], v[102:105], v[28:31], v[6:9]
	v_mfma_f32_16x16x32_bf16 v[6:9], v[226:229], v[18:21], v[82:85]
	v_mfma_f32_16x16x32_bf16 v[126:129], v[198:201], v[28:31], v[6:9]
	v_mfma_f32_16x16x32_bf16 v[6:9], v[98:101], v[188:191], v[78:81]
	v_mfma_f32_16x16x32_bf16 v[134:137], v[102:105], v[14:17], v[46:49]
	v_mfma_f32_16x16x32_bf16 v[46:49], v[102:105], v[192:195], v[6:9]
	v_mfma_f32_16x16x32_bf16 v[6:9], v[226:229], v[188:191], v[152:155]
	v_mfma_f32_16x16x32_bf16 v[122:125], v[198:201], v[192:195], v[6:9]
	v_mfma_f32_16x16x32_bf16 v[6:9], v[98:101], v[242:245], v[156:159]
	v_mfma_f32_16x16x32_bf16 v[16:19], v[102:105], v[246:249], v[6:9]
	v_mfma_f32_16x16x32_bf16 v[6:9], v[226:229], v[242:245], v[160:163]
	v_mfma_f32_16x16x32_bf16 v[118:121], v[198:201], v[246:249], v[6:9]
	s_setprio 0
	s_barrier
	ds_read_b128 v[76:79], v142 offset:49152
	ds_read_b128 v[86:89], v142 offset:50176
	ds_read_b128 v[106:109], v142 offset:51200
	ds_read_b128 v[110:113], v142 offset:52224
	ds_read_b128 v[158:161], v142 offset:53248
	ds_read_b128 v[188:191], v142 offset:54272
	ds_read_b128 v[192:195], v142 offset:55296
	ds_read_b128 v[242:245], v142 offset:56320
	s_barrier
	s_waitcnt lgkmcnt(0)
	s_setprio 1
	s_waitcnt lgkmcnt(0)
	v_mfma_f32_16x16x32_bf16 v[6:9], v[2:5], v[76:79], v[202:205]
	v_mfma_f32_16x16x32_bf16 v[154:157], v[72:75], v[86:89], v[6:9]
	v_mfma_f32_16x16x32_bf16 v[6:9], v[180:183], v[76:79], v[206:209]
	v_mfma_f32_16x16x32_bf16 v[30:33], v[184:187], v[86:89], v[6:9]
	v_mfma_f32_16x16x32_bf16 v[6:9], v[2:5], v[106:109], v[50:53]
	v_mfma_f32_16x16x32_bf16 v[92:95], v[72:75], v[110:113], v[6:9]
	v_mfma_f32_16x16x32_bf16 v[6:9], v[180:183], v[106:109], v[210:213]
	v_mfma_f32_16x16x32_bf16 v[20:23], v[184:187], v[110:113], v[6:9]
	v_mfma_f32_16x16x32_bf16 v[6:9], v[2:5], v[158:161], v[214:217]
	v_mfma_f32_16x16x32_bf16 v[2:5], v[2:5], v[192:195], v[138:141]
	v_mfma_f32_16x16x32_bf16 v[82:85], v[72:75], v[188:191], v[6:9]
	v_mfma_f32_16x16x32_bf16 v[6:9], v[180:183], v[158:161], v[218:221]
	v_mfma_f32_16x16x32_bf16 v[72:75], v[72:75], v[242:245], v[2:5]
	v_mfma_f32_16x16x32_bf16 v[2:5], v[180:183], v[192:195], v[144:147]
	v_mfma_f32_16x16x32_bf16 v[6:9], v[184:187], v[188:191], v[6:9]
	v_mfma_f32_16x16x32_bf16 v[2:5], v[184:187], v[242:245], v[2:5]
	s_setprio 0
	s_setprio 1
	v_mfma_f32_16x16x32_bf16 v[50:53], v[98:101], v[76:79], v[148:151]
	v_mfma_f32_16x16x32_bf16 v[150:153], v[102:105], v[86:89], v[50:53]
	v_mfma_f32_16x16x32_bf16 v[50:53], v[226:229], v[76:79], v[230:233]
	v_mfma_f32_16x16x32_bf16 v[114:117], v[198:201], v[86:89], v[50:53]
	v_mfma_f32_16x16x32_bf16 v[50:53], v[98:101], v[106:109], v[234:237]
	v_mfma_f32_16x16x32_bf16 v[146:149], v[102:105], v[110:113], v[50:53]
	v_mfma_f32_16x16x32_bf16 v[50:53], v[226:229], v[106:109], v[164:167]
	v_mfma_f32_16x16x32_bf16 v[110:113], v[198:201], v[110:113], v[50:53]
	v_mfma_f32_16x16x32_bf16 v[50:53], v[98:101], v[158:161], v[238:241]
	v_mfma_f32_16x16x32_bf16 v[142:145], v[102:105], v[188:191], v[50:53]
	v_mfma_f32_16x16x32_bf16 v[50:53], v[226:229], v[158:161], v[168:171]
	v_mfma_f32_16x16x32_bf16 v[106:109], v[198:201], v[188:191], v[50:53]
	v_mfma_f32_16x16x32_bf16 v[50:53], v[98:101], v[192:195], v[172:175]
	v_mfma_f32_16x16x32_bf16 v[138:141], v[102:105], v[242:245], v[50:53]
	v_mfma_f32_16x16x32_bf16 v[50:53], v[226:229], v[192:195], v[176:179]
	v_mfma_f32_16x16x32_bf16 v[102:105], v[198:201], v[242:245], v[50:53]
	s_setprio 0
	s_cmpk_lt_u32 s1, 0x100
	s_barrier
	s_cbranch_scc0 .LBB0_199
	s_barrier
